# combo21: combo20 + xor-1/2/4/8 steps of the wave reductions (prenorm_rows, prep_tokens sum16, GLA pass C head RMS norm) done with DPP adds (quad_perm / row_half_mirror / row_mirror; same operands, com
# speedup vs baseline: 1.0153x; 1.0051x over previous
; __device__ __forceinline__ float wave_sum(float v) {
; #pragma unroll
;     for (int o = 1; o < 64; o <<= 1) v += __shfl_xor(v, o);
;     return v;
; __device__ __forceinline__ void prenorm_rows(const float* __restrict__ xin, bf16_t* __restrict__ an, float* __restrict__ rss, const float* __restrict__ modl, int coff) {
;     ...
;         const f32x4* xr = (const f32x4*)(xin + (size_t)t * DM) + lane; f32x4 v[4]; float ss = 0.f;
; #pragma unroll
;         for (int j = 0; j < 4; ++j) { v[j] = xr[64 * j]; ss += (v[j][0] * v[j][0] + v[j][1] * v[j][1]) + (v[j][2] * v[j][2] + v[j][3] * v[j][3]); }
;         ss = wave_sum(ss); if (lane == 0) rss[t] = ss;
;         const float* mb = modl + (size_t)(t >> 13) * NMOD;
.LBB0_117:
	global_load_dwordx4 v[0:3], v[24:25], off
	global_load_dwordx4 v[4:7], v[24:25], off offset:1024
	global_load_dwordx4 v[8:11], v[24:25], off offset:2048
	global_load_dwordx4 v[12:15], v[24:25], off offset:3072
	v_ashrrev_i32_e32 v76, 13, v16
	v_mul_i32_i24_e32 v78, 0x1800, v76
	v_ashrrev_i32_e32 v79, 31, v78
	v_lshl_add_u64 v[78:79], v[78:79], 2, s[76:77]
	v_lshl_add_u64 v[80:81], v[78:79], 0, s[12:13]
	v_lshl_add_u64 v[82:83], v[80:81], 0, v[26:27]
	global_load_dwordx4 v[60:63], v[82:83], off
	v_lshl_add_u64 v[82:83], v[80:81], 0, v[28:29]
	global_load_dwordx4 v[64:67], v[82:83], off
	v_lshl_add_u64 v[82:83], v[80:81], 0, v[18:19]
	global_load_dwordx4 v[68:71], v[82:83], off
	v_mov_b32_e32 v84, v30
	v_mov_b32_e32 v85, v19
	v_lshl_add_u64 v[82:83], v[80:81], 0, v[84:85]
	global_load_dwordx4 v[72:75], v[82:83], off
	s_waitcnt vmcnt(7)
	v_mul_f32_e32 v17, v1, v1
	v_mul_f32_e32 v31, v3, v3
	s_waitcnt vmcnt(6)
	v_mul_f32_e32 v38, v5, v5
	v_mul_f32_e32 v39, v7, v7
	s_waitcnt vmcnt(5)
	v_mul_f32_e32 v40, v9, v9
	v_mul_f32_e32 v41, v11, v11
	v_fmac_f32_e32 v17, v0, v0
	v_fmac_f32_e32 v31, v2, v2
	v_fmac_f32_e32 v38, v4, v4
	v_fmac_f32_e32 v39, v6, v6
	s_waitcnt vmcnt(4)
	v_mul_f32_e32 v43, v13, v13
	v_mul_f32_e32 v44, v15, v15
	v_fmac_f32_e32 v40, v8, v8
	v_fmac_f32_e32 v41, v10, v10
	v_add_f32_e32 v17, v17, v31
	v_add_f32_e32 v31, v38, v39
	v_fmac_f32_e32 v43, v12, v12
	v_fmac_f32_e32 v44, v14, v14
	v_add_f32_e32 v38, v40, v41
	v_add_f32_e32 v17, v17, v31
	v_add_f32_e32 v17, v17, v38
	v_add_f32_e32 v31, v43, v44
	v_add_f32_e32 v17, v17, v31
	s_nop 1
	v_add_f32_dpp v17, v17, v17 quad_perm:[1,0,3,2] row_mask:0xf bank_mask:0xf
	s_nop 1
	v_add_f32_dpp v17, v17, v17 quad_perm:[2,3,0,1] row_mask:0xf bank_mask:0xf
	s_nop 1
	v_add_f32_dpp v17, v17, v17 row_half_mirror row_mask:0xf bank_mask:0xf
	s_nop 1
	v_add_f32_dpp v17, v17, v17 row_mirror row_mask:0xf bank_mask:0xf
	s_waitcnt lgkmcnt(0)
	ds_bpermute_b32 v31, v36, v17
	s_waitcnt lgkmcnt(0)
	v_add_f32_e32 v17, v17, v31
	ds_bpermute_b32 v31, v37, v17
	s_waitcnt lgkmcnt(0)
	v_add_f32_e32 v77, v17, v31
	v_lshl_add_u64 v[86:87], s[90:91], 0, v[20:21]
	s_branch .LBB0_116

; __device__ __forceinline__ unsigned pk2(float lo, float hi) { const f32x2 v = {lo, hi}; return __builtin_bit_cast(unsigned, __builtin_convertvector(v, hwbf16x2)); }
; __device__ __forceinline__ float sum16(float v) { v += __shfl_xor(v, 1); v += __shfl_xor(v, 2); v += __shfl_xor(v, 4); v += __shfl_xor(v, 8); return v; }
; __device__ __forceinline__ void prep_tokens(const bf16_t* __restrict__ proj, bf16_t* __restrict__ qn, bf16_t* __restrict__ kvn, bf16_t* __restrict__ Kb, const float* __restrict__ qa, const float* __restrict__ kva, const float* __restrict__ kr, ...
;     ...
;     for (int tg = gw; tg < T / 4; tg += NGW) { const int t = 4 * tg + sub;
;         const bf16_t* pr = proj + (size_t)t * NIN;
;         const u32x4 q0 = *(const u32x4*)(pr + 1536 + 16 * l16), q1 = *(const u32x4*)(pr + 1536 + 16 * l16 + 8);
;         const u32x4 k0 = *(const u32x4*)(pr + 1792 + 8 * l16);
;         const u32x2 p0 = *(const u32x2*)(pr + 1920 + 4 * l16);
;         const f32x4 c4 = *(const f32x4*)(cosT + (size_t)t * 32 + 4 * (l16 & 7)), s4 = *(const f32x4*)(sinT + (size_t)t * 32 + 4 * (l16 & 7));
;         { float f[16]; float ss = 0.f;
; #pragma unroll
;           for (int e2 = 0; e2 < 4; ++e2) { f[2 * e2] = __uint_as_float(q0[e2] << 16); f[2 * e2 + 1] = __uint_as_float(q0[e2] & 0xffff0000u); f[8 + 2 * e2] = __uint_as_float(q1[e2] << 16); f[8 + 2 * e2 + 1] = __uint_as_float(q1[e2] & 0xffff0000u); }
; #pragma unroll
;           for (int e2 = 0; e2 < 16; ++e2) ss += f[e2] * f[e2];
;           const float rr = __builtin_amdgcn_rsqf(sum16(ss) * (1.0f / 256.0f) + EPS);
;           u32x4 o0, o1;
; #pragma unroll
;           for (int e2 = 0; e2 < 4; ++e2) { o0[e2] = pk2(f[2 * e2] * rr * gq[e2 >> 1][2 * (e2 & 1)], f[2 * e2 + 1] * rr * gq[e2 >> 1][2 * (e2 & 1) + 1]);
;                                            o1[e2] = pk2(f[8 + 2 * e2] * rr * gq[2 + (e2 >> 1)][2 * (e2 & 1)], f[8 + 2 * e2 + 1] * rr * gq[2 + (e2 >> 1)][2 * (e2 & 1) + 1]); }
;           *(u32x4*)(qn + (size_t)t * 256 + 16 * l16) = o0; *(u32x4*)(qn + (size_t)t * 256 + 16 * l16 + 8) = o1; }
.LBB0_302:
	v_ashrrev_i32_e32 v39, 31, v38
	v_lshlrev_b64 v[44:45], 12, v[38:39]
	v_lshl_add_u64 v[44:45], s[60:61], 0, v[44:45]
	v_lshl_add_u64 v[56:57], v[44:45], 0, v[160:161]
	global_load_dwordx4 v[52:55], v[56:57], off offset:3072
	s_nop 0
	global_load_dwordx4 v[56:59], v[56:57], off offset:3088
	v_mov_b32_e32 v41, v161
	v_lshl_add_u64 v[60:61], v[44:45], 0, v[40:41]
	global_load_dwordx4 v[60:63], v[60:61], off offset:3584
	v_mov_b32_e32 v43, v161
	v_lshl_add_u64 v[44:45], v[44:45], 0, v[42:43]
	global_load_dwordx2 v[44:45], v[44:45], off offset:3840
	v_lshlrev_b64 v[68:69], 7, v[38:39]
	v_lshl_add_u64 v[64:65], v[28:29], 0, v[68:69]
	v_lshl_add_u64 v[68:69], v[30:31], 0, v[68:69]
	global_load_dwordx4 v[64:67], v[64:65], off
	s_waitcnt vmcnt(4)
	v_lshlrev_b32_e32 v94, 16, v52
	v_and_b32_e32 v95, 0xffff0000, v52
	v_lshlrev_b32_e32 v88, 16, v53
	v_and_b32_e32 v89, 0xffff0000, v53
	v_pk_mul_f32 v[52:53], v[94:95], v[94:95]
	v_pk_mul_f32 v[90:91], v[88:89], v[88:89]
	v_add_f32_e32 v41, v52, v53
	v_lshlrev_b32_e32 v82, 16, v54
	v_and_b32_e32 v83, 0xffff0000, v54
	v_add_f32_e32 v41, v90, v41
	v_lshlrev_b32_e32 v76, 16, v55
	v_and_b32_e32 v77, 0xffff0000, v55
	v_pk_mul_f32 v[54:55], v[82:83], v[82:83]
	v_add_f32_e32 v41, v91, v41
	v_add_f32_e32 v41, v54, v41
	v_pk_mul_f32 v[78:79], v[76:77], v[76:77]
	v_add_f32_e32 v41, v55, v41
	s_waitcnt vmcnt(3)
	v_lshlrev_b32_e32 v92, 16, v56
	v_and_b32_e32 v93, 0xffff0000, v56
	v_add_f32_e32 v41, v78, v41
	v_lshlrev_b32_e32 v84, 16, v57
	v_and_b32_e32 v85, 0xffff0000, v57
	v_pk_mul_f32 v[56:57], v[92:93], v[92:93]
	v_add_f32_e32 v41, v79, v41
	v_add_f32_e32 v41, v56, v41
	v_pk_mul_f32 v[86:87], v[84:85], v[84:85]
	v_add_f32_e32 v41, v57, v41
	v_lshlrev_b32_e32 v80, 16, v58
	v_and_b32_e32 v81, 0xffff0000, v58
	v_add_f32_e32 v41, v86, v41
	v_lshlrev_b32_e32 v72, 16, v59
	v_and_b32_e32 v73, 0xffff0000, v59
	v_pk_mul_f32 v[58:59], v[80:81], v[80:81]
	v_add_f32_e32 v41, v87, v41
	v_add_f32_e32 v41, v58, v41
	v_pk_mul_f32 v[74:75], v[72:73], v[72:73]
	v_add_f32_e32 v41, v59, v41
	v_add_f32_e32 v41, v74, v41
	v_add_f32_e32 v41, v75, v41
	global_load_dwordx4 v[68:71], v[68:69], off
	s_nop 1
	v_add_f32_dpp v41, v41, v41 quad_perm:[1,0,3,2] row_mask:0xf bank_mask:0xf
	s_nop 1
	v_add_f32_dpp v41, v41, v41 quad_perm:[2,3,0,1] row_mask:0xf bank_mask:0xf
	s_nop 1
	v_add_f32_dpp v41, v41, v41 row_half_mirror row_mask:0xf bank_mask:0xf
	s_nop 1
	v_add_f32_dpp v41, v41, v41 row_mirror row_mask:0xf bank_mask:0xf
	s_waitcnt lgkmcnt(0)
	v_fmamk_f32 v41, v41, 0x3b800000, v199
	v_rsq_f32_e32 v74, v41
	s_nop 0
	v_pk_mul_f32 v[54:55], v[74:75], v[92:93] op_sel_hi:[0,1]
	v_pk_mul_f32 v[54:55], v[20:21], v[54:55]
	v_pk_mul_f32 v[52:53], v[74:75], v[94:95] op_sel_hi:[0,1]
	v_cvt_pk_bf16_f32 v56, v54, v55
	v_pk_mul_f32 v[54:55], v[74:75], v[88:89] op_sel_hi:[0,1]
	v_pk_mul_f32 v[52:53], v[12:13], v[52:53]
	v_pk_mul_f32 v[54:55], v[14:15], v[54:55]
	v_cvt_pk_bf16_f32 v52, v52, v53
	v_cvt_pk_bf16_f32 v53, v54, v55
	v_pk_mul_f32 v[54:55], v[74:75], v[84:85] op_sel_hi:[0,1]
	v_pk_mul_f32 v[54:55], v[22:23], v[54:55]
	v_pk_mul_f32 v[58:59], v[74:75], v[80:81] op_sel_hi:[0,1]
	v_pk_mul_f32 v[72:73], v[74:75], v[72:73] op_sel_hi:[0,1]
	v_cvt_pk_bf16_f32 v57, v54, v55
	v_pk_mul_f32 v[54:55], v[74:75], v[82:83] op_sel_hi:[0,1]
	v_pk_mul_f32 v[58:59], v[24:25], v[58:59]
	v_pk_mul_f32 v[76:77], v[74:75], v[76:77] op_sel_hi:[0,1]
	v_pk_mul_f32 v[72:73], v[26:27], v[72:73]
	v_pk_mul_f32 v[54:55], v[16:17], v[54:55]
	v_cvt_pk_bf16_f32 v58, v58, v59
	v_pk_mul_f32 v[76:77], v[18:19], v[76:77]
	v_cvt_pk_bf16_f32 v59, v72, v73
	v_lshlrev_b64 v[72:73], 9, v[38:39]
	v_cvt_pk_bf16_f32 v54, v54, v55
	v_cvt_pk_bf16_f32 v55, v76, v77
	v_lshl_add_u64 v[72:73], v[32:33], 0, v[72:73]
	s_waitcnt vmcnt(3)
; __device__ __forceinline__ unsigned pk2(float lo, float hi) { const f32x2 v = {lo, hi}; return __builtin_bit_cast(unsigned, __builtin_convertvector(v, hwbf16x2)); }
; __device__ __forceinline__ float sum16(float v) { v += __shfl_xor(v, 1); v += __shfl_xor(v, 2); v += __shfl_xor(v, 4); v += __shfl_xor(v, 8); return v; }
; __device__ __forceinline__ void prep_tokens(const bf16_t* __restrict__ proj, bf16_t* __restrict__ qn, bf16_t* __restrict__ kvn, bf16_t* __restrict__ Kb, const float* __restrict__ qa, const float* __restrict__ kva, const float* __restrict__ kr, ...
;     ...
;           *(u32x4*)(qn + (size_t)t * 256 + 16 * l16) = o0; *(u32x4*)(qn + (size_t)t * 256 + 16 * l16 + 8) = o1; }
;         { float f[8]; float ss = 0.f;
; #pragma unroll
;           for (int e2 = 0; e2 < 4; ++e2) { f[2 * e2] = __uint_as_float(k0[e2] << 16); f[2 * e2 + 1] = __uint_as_float(k0[e2] & 0xffff0000u); }
; #pragma unroll
;           for (int e2 = 0; e2 < 8; ++e2) ss += f[e2] * f[e2];
;           const float rr = __builtin_amdgcn_rsqf(sum16(ss) * (1.0f / 128.0f) + EPS);
;           u32x4 o0;
; #pragma unroll
;           for (int e2 = 0; e2 < 4; ++e2) o0[e2] = pk2(f[2 * e2] * rr * gkv[e2 >> 1][2 * (e2 & 1)], f[2 * e2 + 1] * rr * gkv[e2 >> 1][2 * (e2 & 1) + 1]);
;           *(u32x4*)(kvn + (size_t)t * 128 + 8 * l16) = o0; }
;         { float y[4] = {__uint_as_float(p0[0] << 16), __uint_as_float(p0[0] & 0xffff0000u), __uint_as_float(p0[1] << 16), __uint_as_float(p0[1] & 0xffff0000u)};
;           const float rr = __builtin_amdgcn_rsqf(sum16((y[0] * y[0] + y[1] * y[1]) + (y[2] * y[2] + y[3] * y[3])) * (1.0f / 64.0f) + EPS);
;           float ov[4];
; #pragma unroll
;           for (int i = 0; i < 4; ++i) { y[i] = y[i] * rr * gr[i]; const float pn = __shfl_xor(y[i], 8);
;               ov[i] = l16 < 8 ? y[i] * c4[i] - pn * s4[i] : y[i] * c4[i] + pn * s4[i]; }
;           u32x2 w; w.x = pk2(ov[0], ov[1]); w.y = pk2(ov[2], ov[3]);
;           const int b = t >> 13, sp = t & 8191;
; #pragma unroll
;           for (int h = 0; h < 4; ++h) *(u32x2*)(Kb + ((size_t)(b * 4 + h) * SEQ + sp) * 192 + 128 + 4 * l16) = w; }
	v_lshlrev_b32_e32 v74, 16, v60
	v_and_b32_e32 v75, 0xffff0000, v60
	global_store_dwordx4 v[72:73], v[52:55], off
	global_store_dwordx4 v[72:73], v[56:59], off offset:16
	s_nop 0
	v_lshlrev_b32_e32 v54, 16, v62
	v_lshlrev_b32_e32 v56, 16, v63
	v_and_b32_e32 v57, 0xffff0000, v63
	v_and_b32_e32 v55, 0xffff0000, v62
	v_lshlrev_b32_e32 v62, 16, v61
	v_and_b32_e32 v63, 0xffff0000, v61
	v_pk_mul_f32 v[60:61], v[74:75], v[74:75]
	v_pk_mul_f32 v[72:73], v[62:63], v[62:63]
	v_add_f32_e32 v41, v60, v61
	v_add_f32_e32 v41, v72, v41
	v_pk_mul_f32 v[58:59], v[54:55], v[54:55]
	v_add_f32_e32 v41, v73, v41
	v_add_f32_e32 v41, v58, v41
	v_pk_mul_f32 v[52:53], v[56:57], v[56:57]
	v_add_f32_e32 v41, v59, v41
	v_add_f32_e32 v41, v52, v41
	v_add_f32_e32 v41, v53, v41
	s_nop 1
	v_add_f32_dpp v41, v41, v41 quad_perm:[1,0,3,2] row_mask:0xf bank_mask:0xf
	s_nop 1
	v_add_f32_dpp v41, v41, v41 quad_perm:[2,3,0,1] row_mask:0xf bank_mask:0xf
	s_nop 1
	v_add_f32_dpp v41, v41, v41 row_half_mirror row_mask:0xf bank_mask:0xf
	s_nop 1
	v_add_f32_dpp v41, v41, v41 row_mirror row_mask:0xf bank_mask:0xf
	s_waitcnt lgkmcnt(0)
	v_fmamk_f32 v41, v41, 0x3c000000, v199
	v_rsq_f32_e32 v58, v41
	s_nop 0
	v_pk_mul_f32 v[54:55], v[58:59], v[54:55] op_sel_hi:[0,1]
	v_pk_mul_f32 v[56:57], v[58:59], v[56:57] op_sel_hi:[0,1]
	v_pk_mul_f32 v[52:53], v[58:59], v[74:75] op_sel_hi:[0,1]
	v_pk_mul_f32 v[60:61], v[58:59], v[62:63] op_sel_hi:[0,1]
	v_pk_mul_f32 v[54:55], v[8:9], v[54:55]
	v_pk_mul_f32 v[56:57], v[10:11], v[56:57]
	v_pk_mul_f32 v[52:53], v[4:5], v[52:53]
	v_pk_mul_f32 v[60:61], v[6:7], v[60:61]
	v_cvt_pk_bf16_f32 v54, v54, v55
	v_cvt_pk_bf16_f32 v55, v56, v57
	v_lshlrev_b64 v[56:57], 8, v[38:39]
	v_cvt_pk_bf16_f32 v52, v52, v53
	v_cvt_pk_bf16_f32 v53, v60, v61
	v_lshl_add_u64 v[56:57], v[34:35], 0, v[56:57]
	global_store_dwordx4 v[56:57], v[52:55], off
	s_waitcnt vmcnt(5)
	s_nop 0
	v_and_b32_e32 v53, 0xffff0000, v45
	v_and_b32_e32 v55, 0xffff0000, v44
	v_lshlrev_b32_e32 v52, 16, v45
	v_lshlrev_b32_e32 v54, 16, v44
	v_mov_b32_e32 v56, v55
	v_mov_b32_e32 v57, v53
	v_mov_b32_e32 v44, v54
	v_mov_b32_e32 v45, v52
	v_pk_mul_f32 v[56:57], v[56:57], v[56:57]
	s_nop 0
	v_pk_fma_f32 v[44:45], v[44:45], v[44:45], v[56:57]
	s_nop 0
	v_add_f32_e32 v39, v44, v45
	s_nop 1
	v_add_f32_dpp v39, v39, v39 quad_perm:[1,0,3,2] row_mask:0xf bank_mask:0xf
	s_nop 1
	v_add_f32_dpp v39, v39, v39 quad_perm:[2,3,0,1] row_mask:0xf bank_mask:0xf
	s_nop 1
	v_add_f32_dpp v39, v39, v39 row_half_mirror row_mask:0xf bank_mask:0xf
	s_nop 1
	v_add_f32_dpp v39, v39, v39 row_mirror row_mask:0xf bank_mask:0xf
	s_waitcnt lgkmcnt(0)
	v_fmamk_f32 v39, v39, 0x3c800000, v199
	v_rsq_f32_e32 v44, v39
	v_ashrrev_i32_e32 v41, 9, v46
	v_and_b32_e32 v39, 0x1fff, v38
	v_add_u32_e32 v38, 0x2000, v38
	v_pk_mul_f32 v[54:55], v[44:45], v[54:55] op_sel_hi:[0,1]
	v_pk_mul_f32 v[44:45], v[44:45], v[52:53] op_sel_hi:[0,1]
	v_pk_mul_f32 v[44:45], v[2:3], v[44:45]
	ds_bpermute_b32 v52, v50, v44
	ds_bpermute_b32 v53, v50, v45
	v_pk_mul_f32 v[54:55], v[0:1], v[54:55]
	ds_bpermute_b32 v56, v50, v54
	ds_bpermute_b32 v57, v50, v55
	s_waitcnt vmcnt(3) lgkmcnt(2)
	v_pk_mul_f32 v[52:53], v[70:71], v[52:53]
	s_nop 0
	v_cndmask_b32_e64 v53, v53, -v53, vcc
	v_cndmask_b32_e64 v52, v52, -v52, vcc
	s_waitcnt lgkmcnt(0)
	v_pk_mul_f32 v[56:57], v[68:69], v[56:57]
	v_pk_fma_f32 v[52:53], v[66:67], v[44:45], v[52:53]
	v_cndmask_b32_e64 v57, v57, -v57, vcc
	v_cndmask_b32_e64 v56, v56, -v56, vcc
	v_cvt_pk_bf16_f32 v45, v52, v53
	v_and_b32_e32 v52, -4, v41
	v_pk_fma_f32 v[54:55], v[64:65], v[54:55], v[56:57]
	v_ashrrev_i32_e32 v53, 31, v52
	v_cvt_pk_bf16_f32 v44, v54, v55
	v_lshlrev_b64 v[54:55], 13, v[52:53]
	v_or_b32_e32 v43, v54, v39
	v_mad_u64_u32 v[56:57], s[0:1], v43, s67, v[36:37]
	v_or_b32_e32 v54, 1, v52
	v_mad_i32_i24 v57, v55, s67, v57
	v_ashrrev_i32_e32 v55, 31, v54
	v_or_b32_e32 v52, 2, v52
	v_lshlrev_b64 v[54:55], 13, v[54:55]
	v_ashrrev_i32_e32 v53, 31, v52
	v_or_b32_e32 v43, v54, v39
	v_lshlrev_b64 v[52:53], 13, v[52:53]
	global_store_dwordx2 v[56:57], v[44:45], off offset:256
	v_mad_u64_u32 v[56:57], s[0:1], v43, s67, v[36:37]
	v_or_b32_e32 v43, v52, v39
	v_mad_i32_i24 v57, v55, s67, v57
	v_mad_u64_u32 v[54:55], s[0:1], v43, s67, v[36:37]
	v_or_b32_e32 v52, 3, v41
	v_mad_i32_i24 v55, v53, s67, v55
	v_ashrrev_i32_e32 v53, 31, v52
	v_lshlrev_b64 v[52:53], 13, v[52:53]
	v_or_b32_e32 v39, v52, v39
	global_store_dwordx2 v[54:55], v[44:45], off offset:256
	v_mad_u64_u32 v[54:55], s[0:1], v39, s67, v[36:37]
	s_movk_i32 s0, 0x17ff
	v_add_u32_e32 v39, 0x800, v46
	v_cmp_lt_i32_e64 s[0:1], s0, v46
	v_mad_i32_i24 v55, v53, s67, v55
	s_or_b64 s[4:5], s[0:1], s[4:5]
	v_mov_b32_e32 v46, v39
	global_store_dwordx2 v[56:57], v[44:45], off offset:256
	global_store_dwordx2 v[54:55], v[44:45], off offset:256
	s_andn2_b64 exec, exec, s[4:5]
	s_cbranch_execnz .LBB0_302

; #define LAS __attribute__((address_space(3)))
; __device__ __forceinline__ int crow(int r, int hi) { return (r & 3) + 8 * (r >> 2) + 4 * hi; }
; __device__ __forceinline__ float bf2f(unsigned short v) { return __uint_as_float((unsigned)v << 16); }
; __device__ __forceinline__ unsigned f2bf(float f) { return pk2(f, 0.f) & 0xffffu; }
; __device__ __forceinline__ int crow(int r, int hi) { return (r & 3) + 8 * (r >> 2) + 4 * hi; }
; __device__ __forceinline__ float half_sum32(float v) {
; #pragma unroll
;     for (int o = 1; o < 32; o <<= 1) v += __shfl_xor(v, o);
;     return v;
; }
; __device__ __forceinline__ void gla_pass_c(LAS unsigned char* ldsl, const bf16_t* __restrict__ proj, const float* __restrict__ Btab, const float* __restrict__ Gst, const float* __restrict__ gout, bf16_t* __restrict__ mixed) {
;     ...
;         { const bf16_t* gp = proj + (row0 + 32 * tb + crw) * NIN + 1024 + h * 128 + ccl * 8; u32x4 sv[8];
; #pragma unroll
;           for (int i = 0; i < 8; ++i) sv[i] = *(const u32x4*)(gp + (size_t)(4 * i) * NIN);
; #pragma unroll
;           for (int i = 0; i < 8; ++i) *(LAS u32x4*)(Lw + (4 * i + crw) * 256 + ccl * 16) = sv[i]; }
;         float gn[4];
; #pragma unroll
;         for (int dvb = 0; dvb < 4; ++dvb) gn[dvb] = gout[32 * dvb + r];
; #pragma unroll
;         for (int i = 0; i < 16; ++i) { const int tr = crow(i, hh);
;             const float tot = half_sum32((o[0][i] * o[0][i] + o[1][i] * o[1][i]) + (o[2][i] * o[2][i] + o[3][i] * o[3][i]));
;             const float rr = __builtin_amdgcn_rsqf(tot * (1.0f / 128.0f) + EPS);
; #pragma unroll
;             for (int dvb = 0; dvb < 4; ++dvb) { const float g = bf2f(Lh[tr * 128 + 32 * dvb + r]);
;                 const float val = o[dvb][i] * rr * gn[dvb] * (g * __builtin_amdgcn_rcpf(1.0f + __expf(-g)));
;                 Lh[(32 + tr) * 128 + 32 * dvb + r] = (bf16_t)f2bf(val); } }
.LBB0_873:
	v_or3_b32 v122, s2, v110, v122
	v_lshlrev_b64 v[64:65], 12, v[122:123]
	v_lshl_add_u64 v[64:65], s[60:61], 0, v[64:65]
	v_lshlrev_b32_e32 v160, 1, v124
	v_lshl_add_u64 v[64:65], v[64:65], 0, v[160:161]
	v_mov_b32_e32 v121, v161
	v_lshl_add_u64 v[92:93], v[64:65], 0, v[120:121]
	v_add_co_u32_e32 v68, vcc, 0x4000, v92
	global_load_dwordx4 v[64:67], v[92:93], off offset:2048
	s_nop 0
	v_addc_co_u32_e32 v69, vcc, 0, v93, vcc
	v_add_co_u32_e32 v72, vcc, 0x8000, v92
	global_load_dwordx4 v[68:71], v[68:69], off offset:2048
	s_nop 0
	v_addc_co_u32_e32 v73, vcc, 0, v93, vcc
	v_add_co_u32_e32 v76, vcc, 0xc000, v92
	global_load_dwordx4 v[72:75], v[72:73], off offset:2048
	s_nop 0
	v_addc_co_u32_e32 v77, vcc, 0, v93, vcc
	v_add_co_u32_e32 v80, vcc, s51, v92
	s_mov_b32 s33, 0x18000
	s_nop 0
	v_addc_co_u32_e32 v81, vcc, 0, v93, vcc
	v_add_co_u32_e32 v84, vcc, s52, v92
	global_load_dwordx4 v[76:79], v[76:77], off offset:2048
	s_nop 0
	v_addc_co_u32_e32 v85, vcc, 0, v93, vcc
	v_add_co_u32_e32 v88, vcc, s33, v92
	global_load_dwordx4 v[80:83], v[80:81], off offset:2048
	s_nop 0
	v_addc_co_u32_e32 v89, vcc, 0, v93, vcc
	s_mov_b32 s2, 0x1c000
	global_load_dwordx4 v[84:87], v[84:85], off offset:2048
	v_add_co_u32_e32 v92, vcc, s2, v92
	global_load_dwordx4 v[88:91], v[88:89], off offset:2048
	s_nop 0
	v_addc_co_u32_e32 v93, vcc, 0, v93, vcc
	global_load_dwordx4 v[92:95], v[92:93], off offset:2048
	s_movk_i32 s2, 0x2000
	s_mov_b32 s42, 0x8000
	s_waitcnt vmcnt(7)
	ds_write_b128 v140, v[64:67]
	s_waitcnt vmcnt(6)
	ds_write_b128 v140, v[68:71] offset:1024
	s_waitcnt vmcnt(5)
	ds_write_b128 v140, v[72:75] offset:2048
	s_waitcnt vmcnt(4)
	ds_write_b128 v140, v[76:79] offset:3072
	s_waitcnt vmcnt(3)
	ds_write_b128 v140, v[80:83] offset:4096
	s_waitcnt vmcnt(2)
	ds_write_b128 v140, v[84:87] offset:5120
	s_waitcnt vmcnt(1)
	ds_write_b128 v140, v[88:91] offset:6144
	s_waitcnt vmcnt(0)
	ds_write_b128 v140, v[92:95] offset:7168
	v_mul_f32_e32 v64, v16, v16
	v_mul_f32_e32 v65, v32, v32
	v_fmac_f32_e32 v64, v0, v0
	v_fmac_f32_e32 v65, v48, v48
	v_add_f32_e32 v64, v64, v65
	s_nop 1
	v_add_f32_dpp v64, v64, v64 quad_perm:[1,0,3,2] row_mask:0xf bank_mask:0xf
	s_nop 1
	v_add_f32_dpp v64, v64, v64 quad_perm:[2,3,0,1] row_mask:0xf bank_mask:0xf
	s_nop 1
	v_add_f32_dpp v64, v64, v64 row_half_mirror row_mask:0xf bank_mask:0xf
	s_nop 1
	v_add_f32_dpp v64, v64, v64 row_mirror row_mask:0xf bank_mask:0xf
	s_waitcnt lgkmcnt(0)
	ds_bpermute_b32 v65, v137, v64
	s_waitcnt lgkmcnt(0)
	v_add_f32_e32 v64, v64, v65
	ds_read_u16 v65, v138
	v_fmamk_f32 v64, v64, 0x3c000000, v199
	v_rsq_f32_e32 v64, v64
	s_waitcnt lgkmcnt(0)
	v_lshlrev_b32_e32 v65, 16, v65
	v_mul_f32_e32 v66, 0xbfb8aa3b, v65
	v_exp_f32_e32 v66, v66
	v_mul_f32_e32 v0, v0, v64
	v_mul_f32_e32 v0, v113, v0
	v_mul_f32_e32 v16, v16, v64
	v_add_f32_e32 v66, 1.0, v66
	v_rcp_f32_e32 v66, v66
	v_mul_f32_e32 v16, v130, v16
	v_mul_f32_e32 v65, v66, v65
	v_mul_f32_e32 v0, v0, v65
	v_cvt_pk_bf16_f32 v0, v0, s0
	ds_write_b16 v138, v0 offset:8192
	ds_read_u16 v0, v138 offset:64
	s_waitcnt lgkmcnt(0)
	v_lshlrev_b32_e32 v0, 16, v0
	v_mul_f32_e32 v65, 0xbfb8aa3b, v0
	v_exp_f32_e32 v65, v65
	s_nop 0
	v_add_f32_e32 v65, 1.0, v65
	v_rcp_f32_e32 v65, v65
	s_nop 0
	v_mul_f32_e32 v0, v65, v0
	v_mul_f32_e32 v0, v16, v0
	v_cvt_pk_bf16_f32 v0, v0, s0
	ds_write_b16 v138, v0 offset:8256
	ds_read_u16 v0, v138 offset:128
	v_mul_f32_e32 v16, v48, v64
	v_mul_f32_e32 v16, v131, v16
	s_waitcnt lgkmcnt(0)
	v_lshlrev_b32_e32 v0, 16, v0
	v_mul_f32_e32 v48, 0xbfb8aa3b, v0
	v_exp_f32_e32 v48, v48
	s_nop 0
	v_add_f32_e32 v48, 1.0, v48
	v_rcp_f32_e32 v48, v48
	s_nop 0
	v_mul_f32_e32 v0, v48, v0
	v_mul_f32_e32 v0, v16, v0
	v_cvt_pk_bf16_f32 v0, v0, s0
	ds_write_b16 v138, v0 offset:8320
	ds_read_u16 v0, v138 offset:192
	v_mul_f32_e32 v16, v32, v64
	v_mul_f32_e32 v16, v132, v16
	s_waitcnt lgkmcnt(0)
	v_lshlrev_b32_e32 v0, 16, v0
	v_mul_f32_e32 v32, 0xbfb8aa3b, v0
	v_exp_f32_e32 v32, v32
	s_nop 0
	v_add_f32_e32 v32, 1.0, v32
	v_rcp_f32_e32 v32, v32
	s_nop 0
	v_mul_f32_e32 v0, v32, v0
	v_mul_f32_e32 v0, v16, v0
	v_cvt_pk_bf16_f32 v0, v0, s0
	ds_write_b16 v138, v0 offset:8384
	v_mul_f32_e32 v0, v17, v17
	v_mul_f32_e32 v16, v33, v33
	v_fmac_f32_e32 v0, v1, v1
	v_fmac_f32_e32 v16, v49, v49
	v_add_f32_e32 v0, v0, v16
	s_nop 1
	v_add_f32_dpp v0, v0, v0 quad_perm:[1,0,3,2] row_mask:0xf bank_mask:0xf
	s_nop 1
	v_add_f32_dpp v0, v0, v0 quad_perm:[2,3,0,1] row_mask:0xf bank_mask:0xf
	s_nop 1
	v_add_f32_dpp v0, v0, v0 row_half_mirror row_mask:0xf bank_mask:0xf
	s_nop 1
	v_add_f32_dpp v0, v0, v0 row_mirror row_mask:0xf bank_mask:0xf
	s_waitcnt lgkmcnt(0)
	ds_bpermute_b32 v16, v137, v0
	s_waitcnt lgkmcnt(0)
	v_add_f32_e32 v0, v0, v16
	ds_read_u16 v16, v138 offset:256
	v_fmamk_f32 v0, v0, 0x3c000000, v199
	v_rsq_f32_e32 v0, v0
	s_waitcnt lgkmcnt(0)
	v_lshlrev_b32_e32 v16, 16, v16
	v_mul_f32_e32 v32, 0xbfb8aa3b, v16
	v_exp_f32_e32 v32, v32
	v_mul_f32_e32 v1, v1, v0
	v_mul_f32_e32 v1, v113, v1
	v_add_f32_e32 v32, 1.0, v32
	v_rcp_f32_e32 v32, v32
	s_nop 0
	v_mul_f32_e32 v16, v32, v16
	v_mul_f32_e32 v1, v1, v16
	v_cvt_pk_bf16_f32 v1, v1, s0
	ds_write_b16 v138, v1 offset:8448
	ds_read_u16 v1, v138 offset:320
	v_mul_f32_e32 v16, v17, v0
	v_mul_f32_e32 v16, v130, v16
	s_waitcnt lgkmcnt(0)
	v_lshlrev_b32_e32 v1, 16, v1
	v_mul_f32_e32 v17, 0xbfb8aa3b, v1
	v_exp_f32_e32 v17, v17
	s_nop 0
	v_add_f32_e32 v17, 1.0, v17
	v_rcp_f32_e32 v17, v17
	s_nop 0
	v_mul_f32_e32 v1, v17, v1
	v_mul_f32_e32 v1, v16, v1
	v_cvt_pk_bf16_f32 v1, v1, s0
	ds_write_b16 v138, v1 offset:8512
	ds_read_u16 v1, v138 offset:384
	v_mul_f32_e32 v16, v49, v0
	v_mul_f32_e32 v16, v131, v16
	v_mul_f32_e32 v0, v33, v0
	v_mul_f32_e32 v0, v132, v0
	s_waitcnt lgkmcnt(0)
; __device__ __forceinline__ int crow(int r, int hi) { return (r & 3) + 8 * (r >> 2) + 4 * hi; }
; __device__ __forceinline__ float bf2f(unsigned short v) { return __uint_as_float((unsigned)v << 16); }
; __device__ __forceinline__ unsigned f2bf(float f) { return pk2(f, 0.f) & 0xffffu; }
; __device__ __forceinline__ int crow(int r, int hi) { return (r & 3) + 8 * (r >> 2) + 4 * hi; }
; __device__ __forceinline__ float half_sum32(float v) {
; #pragma unroll
;     for (int o = 1; o < 32; o <<= 1) v += __shfl_xor(v, o);
;     return v;
; }
; __device__ __forceinline__ void gla_pass_c(LAS unsigned char* ldsl, const bf16_t* __restrict__ proj, const float* __restrict__ Btab, const float* __restrict__ Gst, const float* __restrict__ gout, bf16_t* __restrict__ mixed) {
;     ...
;         for (int i = 0; i < 16; ++i) { const int tr = crow(i, hh);
;             const float tot = half_sum32((o[0][i] * o[0][i] + o[1][i] * o[1][i]) + (o[2][i] * o[2][i] + o[3][i] * o[3][i]));
;             const float rr = __builtin_amdgcn_rsqf(tot * (1.0f / 128.0f) + EPS);
; #pragma unroll
;             for (int dvb = 0; dvb < 4; ++dvb) { const float g = bf2f(Lh[tr * 128 + 32 * dvb + r]);
;                 const float val = o[dvb][i] * rr * gn[dvb] * (g * __builtin_amdgcn_rcpf(1.0f + __expf(-g)));
;                 Lh[(32 + tr) * 128 + 32 * dvb + r] = (bf16_t)f2bf(val); } }
	v_lshlrev_b32_e32 v1, 16, v1
	v_mul_f32_e32 v17, 0xbfb8aa3b, v1
	v_exp_f32_e32 v17, v17
	s_nop 0
	v_add_f32_e32 v17, 1.0, v17
	v_rcp_f32_e32 v17, v17
	s_nop 0
	v_mul_f32_e32 v1, v17, v1
	v_mul_f32_e32 v1, v16, v1
	v_cvt_pk_bf16_f32 v1, v1, s0
	ds_write_b16 v138, v1 offset:8576
	ds_read_u16 v1, v138 offset:448
	s_waitcnt lgkmcnt(0)
	v_lshlrev_b32_e32 v1, 16, v1
	v_mul_f32_e32 v16, 0xbfb8aa3b, v1
	v_exp_f32_e32 v16, v16
	s_nop 0
	v_add_f32_e32 v16, 1.0, v16
	v_rcp_f32_e32 v16, v16
	s_nop 0
	v_mul_f32_e32 v1, v16, v1
	v_mul_f32_e32 v0, v0, v1
	v_cvt_pk_bf16_f32 v0, v0, s0
	ds_write_b16 v138, v0 offset:8640
	v_mul_f32_e32 v0, v18, v18
	v_mul_f32_e32 v1, v34, v34
	v_fmac_f32_e32 v0, v2, v2
	v_fmac_f32_e32 v1, v50, v50
	v_add_f32_e32 v0, v0, v1
	s_nop 1
	v_add_f32_dpp v0, v0, v0 quad_perm:[1,0,3,2] row_mask:0xf bank_mask:0xf
	s_nop 1
	v_add_f32_dpp v0, v0, v0 quad_perm:[2,3,0,1] row_mask:0xf bank_mask:0xf
	s_nop 1
	v_add_f32_dpp v0, v0, v0 row_half_mirror row_mask:0xf bank_mask:0xf
	s_nop 1
	v_add_f32_dpp v0, v0, v0 row_mirror row_mask:0xf bank_mask:0xf
	s_waitcnt lgkmcnt(0)
	ds_bpermute_b32 v1, v137, v0
	s_waitcnt lgkmcnt(0)
	v_add_f32_e32 v0, v0, v1
	ds_read_u16 v1, v138 offset:512
	v_fmamk_f32 v0, v0, 0x3c000000, v199
	v_rsq_f32_e32 v0, v0
	s_waitcnt lgkmcnt(0)
	v_lshlrev_b32_e32 v1, 16, v1
	v_mul_f32_e32 v16, 0xbfb8aa3b, v1
	v_exp_f32_e32 v16, v16
	v_mul_f32_e32 v2, v2, v0
	v_mul_f32_e32 v2, v113, v2
	v_add_f32_e32 v16, 1.0, v16
	v_rcp_f32_e32 v16, v16
	s_nop 0
	v_mul_f32_e32 v1, v16, v1
	v_mul_f32_e32 v1, v2, v1
	v_cvt_pk_bf16_f32 v1, v1, s0
	ds_write_b16 v138, v1 offset:8704
	ds_read_u16 v1, v138 offset:576
	v_mul_f32_e32 v2, v18, v0
	v_mul_f32_e32 v2, v130, v2
	s_waitcnt lgkmcnt(0)
	v_lshlrev_b32_e32 v1, 16, v1
	v_mul_f32_e32 v16, 0xbfb8aa3b, v1
	v_exp_f32_e32 v16, v16
	s_nop 0
	v_add_f32_e32 v16, 1.0, v16
	v_rcp_f32_e32 v16, v16
	s_nop 0
	v_mul_f32_e32 v1, v16, v1
	v_mul_f32_e32 v1, v2, v1
	v_cvt_pk_bf16_f32 v1, v1, s0
	ds_write_b16 v138, v1 offset:8768
	ds_read_u16 v1, v138 offset:640
	v_mul_f32_e32 v2, v50, v0
	v_mul_f32_e32 v2, v131, v2
	v_mul_f32_e32 v0, v34, v0
	v_mul_f32_e32 v0, v132, v0
	s_waitcnt lgkmcnt(0)
	v_lshlrev_b32_e32 v1, 16, v1
	v_mul_f32_e32 v16, 0xbfb8aa3b, v1
	v_exp_f32_e32 v16, v16
	s_nop 0
	v_add_f32_e32 v16, 1.0, v16
	v_rcp_f32_e32 v16, v16
	s_nop 0
	v_mul_f32_e32 v1, v16, v1
	v_mul_f32_e32 v1, v2, v1
	v_cvt_pk_bf16_f32 v1, v1, s0
	ds_write_b16 v138, v1 offset:8832
	ds_read_u16 v1, v138 offset:704
	s_waitcnt lgkmcnt(0)
	v_lshlrev_b32_e32 v1, 16, v1
	v_mul_f32_e32 v2, 0xbfb8aa3b, v1
	v_exp_f32_e32 v2, v2
	s_nop 0
	v_add_f32_e32 v2, 1.0, v2
	v_rcp_f32_e32 v2, v2
	s_nop 0
	v_mul_f32_e32 v1, v2, v1
	v_mul_f32_e32 v0, v0, v1
	v_cvt_pk_bf16_f32 v0, v0, s0
	ds_write_b16 v138, v0 offset:8896
	v_mul_f32_e32 v0, v19, v19
	v_mul_f32_e32 v1, v35, v35
	v_fmac_f32_e32 v0, v3, v3
	v_fmac_f32_e32 v1, v51, v51
	v_add_f32_e32 v0, v0, v1
	s_nop 1
	v_add_f32_dpp v0, v0, v0 quad_perm:[1,0,3,2] row_mask:0xf bank_mask:0xf
	s_nop 1
	v_add_f32_dpp v0, v0, v0 quad_perm:[2,3,0,1] row_mask:0xf bank_mask:0xf
	s_nop 1
	v_add_f32_dpp v0, v0, v0 row_half_mirror row_mask:0xf bank_mask:0xf
	s_nop 1
	v_add_f32_dpp v0, v0, v0 row_mirror row_mask:0xf bank_mask:0xf
	s_waitcnt lgkmcnt(0)
	ds_bpermute_b32 v1, v137, v0
	s_waitcnt lgkmcnt(0)
	v_add_f32_e32 v0, v0, v1
	ds_read_u16 v1, v138 offset:768
	v_fmamk_f32 v0, v0, 0x3c000000, v199
	v_rsq_f32_e32 v0, v0
	s_waitcnt lgkmcnt(0)
	v_lshlrev_b32_e32 v1, 16, v1
	v_mul_f32_e32 v2, v3, v0
	v_mul_f32_e32 v3, 0xbfb8aa3b, v1
	v_exp_f32_e32 v3, v3
	v_mul_f32_e32 v2, v113, v2
	v_add_f32_e32 v3, 1.0, v3
	v_rcp_f32_e32 v3, v3
	s_nop 0
	v_mul_f32_e32 v1, v3, v1
	v_mul_f32_e32 v1, v2, v1
	v_cvt_pk_bf16_f32 v1, v1, s0
	ds_write_b16 v138, v1 offset:8960
	ds_read_u16 v1, v138 offset:832
	v_mul_f32_e32 v2, v19, v0
	v_mul_f32_e32 v2, v130, v2
	s_waitcnt lgkmcnt(0)
	v_lshlrev_b32_e32 v1, 16, v1
	v_mul_f32_e32 v3, 0xbfb8aa3b, v1
	v_exp_f32_e32 v3, v3
	s_nop 0
	v_add_f32_e32 v3, 1.0, v3
	v_rcp_f32_e32 v3, v3
	s_nop 0
	v_mul_f32_e32 v1, v3, v1
	v_mul_f32_e32 v1, v2, v1
	v_cvt_pk_bf16_f32 v1, v1, s0
	ds_write_b16 v138, v1 offset:9024
	ds_read_u16 v1, v138 offset:896
	v_mul_f32_e32 v2, v51, v0
	v_mul_f32_e32 v2, v131, v2
	v_mul_f32_e32 v0, v35, v0
	v_mul_f32_e32 v0, v132, v0
	s_waitcnt lgkmcnt(0)
	v_lshlrev_b32_e32 v1, 16, v1
	v_mul_f32_e32 v3, 0xbfb8aa3b, v1
	v_exp_f32_e32 v3, v3
	s_nop 0
	v_add_f32_e32 v3, 1.0, v3
	v_rcp_f32_e32 v3, v3
	s_nop 0
	v_mul_f32_e32 v1, v3, v1
	v_mul_f32_e32 v1, v2, v1
	v_cvt_pk_bf16_f32 v1, v1, s0
	ds_write_b16 v138, v1 offset:9088
	ds_read_u16 v1, v138 offset:960
	s_waitcnt lgkmcnt(0)
	v_lshlrev_b32_e32 v1, 16, v1
	v_mul_f32_e32 v2, 0xbfb8aa3b, v1
	v_exp_f32_e32 v2, v2
	s_nop 0
	v_add_f32_e32 v2, 1.0, v2
	v_rcp_f32_e32 v2, v2
	s_nop 0
	v_mul_f32_e32 v1, v2, v1
	v_mul_f32_e32 v0, v0, v1
	v_cvt_pk_bf16_f32 v0, v0, s0
	ds_write_b16 v138, v0 offset:9152
	v_mul_f32_e32 v0, v20, v20
	v_mul_f32_e32 v1, v36, v36
	v_fmac_f32_e32 v0, v4, v4
	v_fmac_f32_e32 v1, v52, v52
	v_add_f32_e32 v0, v0, v1
	s_nop 1
	v_add_f32_dpp v0, v0, v0 quad_perm:[1,0,3,2] row_mask:0xf bank_mask:0xf
	s_nop 1
	v_add_f32_dpp v0, v0, v0 quad_perm:[2,3,0,1] row_mask:0xf bank_mask:0xf
	s_nop 1
	v_add_f32_dpp v0, v0, v0 row_half_mirror row_mask:0xf bank_mask:0xf
	s_nop 1
	v_add_f32_dpp v0, v0, v0 row_mirror row_mask:0xf bank_mask:0xf
	s_waitcnt lgkmcnt(0)
	ds_bpermute_b32 v1, v137, v0
	s_waitcnt lgkmcnt(0)
	v_add_f32_e32 v0, v0, v1
	ds_read_u16 v1, v138 offset:2048
	v_fmamk_f32 v0, v0, 0x3c000000, v199
	v_rsq_f32_e32 v0, v0
	s_waitcnt lgkmcnt(0)
; __device__ __forceinline__ int crow(int r, int hi) { return (r & 3) + 8 * (r >> 2) + 4 * hi; }
; __device__ __forceinline__ float bf2f(unsigned short v) { return __uint_as_float((unsigned)v << 16); }
; __device__ __forceinline__ unsigned f2bf(float f) { return pk2(f, 0.f) & 0xffffu; }
; __device__ __forceinline__ int crow(int r, int hi) { return (r & 3) + 8 * (r >> 2) + 4 * hi; }
; __device__ __forceinline__ float half_sum32(float v) {
; #pragma unroll
;     for (int o = 1; o < 32; o <<= 1) v += __shfl_xor(v, o);
;     return v;
; }
; __device__ __forceinline__ void gla_pass_c(LAS unsigned char* ldsl, const bf16_t* __restrict__ proj, const float* __restrict__ Btab, const float* __restrict__ Gst, const float* __restrict__ gout, bf16_t* __restrict__ mixed) {
;     ...
;         for (int i = 0; i < 16; ++i) { const int tr = crow(i, hh);
;             const float tot = half_sum32((o[0][i] * o[0][i] + o[1][i] * o[1][i]) + (o[2][i] * o[2][i] + o[3][i] * o[3][i]));
;             const float rr = __builtin_amdgcn_rsqf(tot * (1.0f / 128.0f) + EPS);
; #pragma unroll
;             for (int dvb = 0; dvb < 4; ++dvb) { const float g = bf2f(Lh[tr * 128 + 32 * dvb + r]);
;                 const float val = o[dvb][i] * rr * gn[dvb] * (g * __builtin_amdgcn_rcpf(1.0f + __expf(-g)));
;                 Lh[(32 + tr) * 128 + 32 * dvb + r] = (bf16_t)f2bf(val); } }
	v_lshlrev_b32_e32 v1, 16, v1
	v_mul_f32_e32 v3, 0xbfb8aa3b, v1
	v_exp_f32_e32 v3, v3
	v_mul_f32_e32 v2, v4, v0
	v_mul_f32_e32 v2, v113, v2
	v_add_f32_e32 v3, 1.0, v3
	v_rcp_f32_e32 v3, v3
	s_nop 0
	v_mul_f32_e32 v1, v3, v1
	v_mul_f32_e32 v1, v2, v1
	v_cvt_pk_bf16_f32 v1, v1, s0
	ds_write_b16 v138, v1 offset:10240
	ds_read_u16 v1, v138 offset:2112
	v_mul_f32_e32 v2, v20, v0
	v_mul_f32_e32 v2, v130, v2
	s_waitcnt lgkmcnt(0)
	v_lshlrev_b32_e32 v1, 16, v1
	v_mul_f32_e32 v3, 0xbfb8aa3b, v1
	v_exp_f32_e32 v3, v3
	s_nop 0
	v_add_f32_e32 v3, 1.0, v3
	v_rcp_f32_e32 v3, v3
	s_nop 0
	v_mul_f32_e32 v1, v3, v1
	v_mul_f32_e32 v1, v2, v1
	v_cvt_pk_bf16_f32 v1, v1, s0
	ds_write_b16 v138, v1 offset:10304
	ds_read_u16 v1, v138 offset:2176
	v_mul_f32_e32 v2, v52, v0
	v_mul_f32_e32 v2, v131, v2
	v_mul_f32_e32 v0, v36, v0
	v_mul_f32_e32 v0, v132, v0
	s_waitcnt lgkmcnt(0)
	v_lshlrev_b32_e32 v1, 16, v1
	v_mul_f32_e32 v3, 0xbfb8aa3b, v1
	v_exp_f32_e32 v3, v3
	s_nop 0
	v_add_f32_e32 v3, 1.0, v3
	v_rcp_f32_e32 v3, v3
	s_nop 0
	v_mul_f32_e32 v1, v3, v1
	v_mul_f32_e32 v1, v2, v1
	v_cvt_pk_bf16_f32 v1, v1, s0
	ds_write_b16 v138, v1 offset:10368
	ds_read_u16 v1, v138 offset:2240
	s_waitcnt lgkmcnt(0)
	v_lshlrev_b32_e32 v1, 16, v1
	v_mul_f32_e32 v2, 0xbfb8aa3b, v1
	v_exp_f32_e32 v2, v2
	s_nop 0
	v_add_f32_e32 v2, 1.0, v2
	v_rcp_f32_e32 v2, v2
	s_nop 0
	v_mul_f32_e32 v1, v2, v1
	v_mul_f32_e32 v0, v0, v1
	v_cvt_pk_bf16_f32 v0, v0, s0
	ds_write_b16 v138, v0 offset:10432
	v_mul_f32_e32 v0, v21, v21
	v_mul_f32_e32 v1, v37, v37
	v_fmac_f32_e32 v0, v5, v5
	v_fmac_f32_e32 v1, v53, v53
	v_add_f32_e32 v0, v0, v1
	s_nop 1
	v_add_f32_dpp v0, v0, v0 quad_perm:[1,0,3,2] row_mask:0xf bank_mask:0xf
	s_nop 1
	v_add_f32_dpp v0, v0, v0 quad_perm:[2,3,0,1] row_mask:0xf bank_mask:0xf
	s_nop 1
	v_add_f32_dpp v0, v0, v0 row_half_mirror row_mask:0xf bank_mask:0xf
	s_nop 1
	v_add_f32_dpp v0, v0, v0 row_mirror row_mask:0xf bank_mask:0xf
	s_waitcnt lgkmcnt(0)
	ds_bpermute_b32 v1, v137, v0
	s_waitcnt lgkmcnt(0)
	v_add_f32_e32 v0, v0, v1
	ds_read_u16 v1, v138 offset:2304
	v_fmamk_f32 v0, v0, 0x3c000000, v199
	v_rsq_f32_e32 v0, v0
	s_waitcnt lgkmcnt(0)
	v_lshlrev_b32_e32 v1, 16, v1
	v_mul_f32_e32 v3, 0xbfb8aa3b, v1
	v_exp_f32_e32 v3, v3
	v_mul_f32_e32 v2, v5, v0
	v_mul_f32_e32 v2, v113, v2
	v_add_f32_e32 v3, 1.0, v3
	v_rcp_f32_e32 v3, v3
	s_nop 0
	v_mul_f32_e32 v1, v3, v1
	v_mul_f32_e32 v1, v2, v1
	v_cvt_pk_bf16_f32 v1, v1, s0
	ds_write_b16 v138, v1 offset:10496
	ds_read_u16 v1, v138 offset:2368
	v_mul_f32_e32 v2, v21, v0
	v_mul_f32_e32 v2, v130, v2
	s_waitcnt lgkmcnt(0)
	v_lshlrev_b32_e32 v1, 16, v1
	v_mul_f32_e32 v3, 0xbfb8aa3b, v1
	v_exp_f32_e32 v3, v3
	s_nop 0
	v_add_f32_e32 v3, 1.0, v3
	v_rcp_f32_e32 v3, v3
	s_nop 0
	v_mul_f32_e32 v1, v3, v1
	v_mul_f32_e32 v1, v2, v1
	v_cvt_pk_bf16_f32 v1, v1, s0
	ds_write_b16 v138, v1 offset:10560
	ds_read_u16 v1, v138 offset:2432
	v_mul_f32_e32 v2, v53, v0
	v_mul_f32_e32 v2, v131, v2
	v_mul_f32_e32 v0, v37, v0
	v_mul_f32_e32 v0, v132, v0
	s_waitcnt lgkmcnt(0)
	v_lshlrev_b32_e32 v1, 16, v1
	v_mul_f32_e32 v3, 0xbfb8aa3b, v1
	v_exp_f32_e32 v3, v3
	s_nop 0
	v_add_f32_e32 v3, 1.0, v3
	v_rcp_f32_e32 v3, v3
	s_nop 0
	v_mul_f32_e32 v1, v3, v1
	v_mul_f32_e32 v1, v2, v1
	v_cvt_pk_bf16_f32 v1, v1, s0
	ds_write_b16 v138, v1 offset:10624
	ds_read_u16 v1, v138 offset:2496
	s_waitcnt lgkmcnt(0)
	v_lshlrev_b32_e32 v1, 16, v1
	v_mul_f32_e32 v2, 0xbfb8aa3b, v1
	v_exp_f32_e32 v2, v2
	s_nop 0
	v_add_f32_e32 v2, 1.0, v2
	v_rcp_f32_e32 v2, v2
	s_nop 0
	v_mul_f32_e32 v1, v2, v1
	v_mul_f32_e32 v0, v0, v1
	v_cvt_pk_bf16_f32 v0, v0, s0
	ds_write_b16 v138, v0 offset:10688
	v_mul_f32_e32 v0, v22, v22
	v_mul_f32_e32 v1, v38, v38
	v_fmac_f32_e32 v0, v6, v6
	v_fmac_f32_e32 v1, v54, v54
	v_add_f32_e32 v0, v0, v1
	s_nop 1
	v_add_f32_dpp v0, v0, v0 quad_perm:[1,0,3,2] row_mask:0xf bank_mask:0xf
	s_nop 1
	v_add_f32_dpp v0, v0, v0 quad_perm:[2,3,0,1] row_mask:0xf bank_mask:0xf
	s_nop 1
	v_add_f32_dpp v0, v0, v0 row_half_mirror row_mask:0xf bank_mask:0xf
	s_nop 1
	v_add_f32_dpp v0, v0, v0 row_mirror row_mask:0xf bank_mask:0xf
	s_waitcnt lgkmcnt(0)
	ds_bpermute_b32 v1, v137, v0
	s_waitcnt lgkmcnt(0)
	v_add_f32_e32 v0, v0, v1
	ds_read_u16 v1, v138 offset:2560
	v_fmamk_f32 v0, v0, 0x3c000000, v199
	v_rsq_f32_e32 v0, v0
	s_waitcnt lgkmcnt(0)
	v_lshlrev_b32_e32 v1, 16, v1
	v_mul_f32_e32 v3, 0xbfb8aa3b, v1
	v_exp_f32_e32 v3, v3
	v_mul_f32_e32 v2, v6, v0
	v_mul_f32_e32 v2, v113, v2
	v_add_f32_e32 v3, 1.0, v3
	v_rcp_f32_e32 v3, v3
	s_nop 0
	v_mul_f32_e32 v1, v3, v1
	v_mul_f32_e32 v1, v2, v1
	v_cvt_pk_bf16_f32 v1, v1, s0
	ds_write_b16 v138, v1 offset:10752
	ds_read_u16 v1, v138 offset:2624
	v_mul_f32_e32 v2, v22, v0
	v_mul_f32_e32 v2, v130, v2
	s_waitcnt lgkmcnt(0)
	v_lshlrev_b32_e32 v1, 16, v1
	v_mul_f32_e32 v3, 0xbfb8aa3b, v1
	v_exp_f32_e32 v3, v3
	s_nop 0
	v_add_f32_e32 v3, 1.0, v3
	v_rcp_f32_e32 v3, v3
	s_nop 0
	v_mul_f32_e32 v1, v3, v1
	v_mul_f32_e32 v1, v2, v1
	v_cvt_pk_bf16_f32 v1, v1, s0
	ds_write_b16 v138, v1 offset:10816
	ds_read_u16 v1, v138 offset:2688
	v_mul_f32_e32 v2, v54, v0
	v_mul_f32_e32 v2, v131, v2
	v_mul_f32_e32 v0, v38, v0
	v_mul_f32_e32 v0, v132, v0
	s_waitcnt lgkmcnt(0)
	v_lshlrev_b32_e32 v1, 16, v1
	v_mul_f32_e32 v3, 0xbfb8aa3b, v1
	v_exp_f32_e32 v3, v3
	s_nop 0
	v_add_f32_e32 v3, 1.0, v3
	v_rcp_f32_e32 v3, v3
	s_nop 0
	v_mul_f32_e32 v1, v3, v1
	v_mul_f32_e32 v1, v2, v1
	v_cvt_pk_bf16_f32 v1, v1, s0
	ds_write_b16 v138, v1 offset:10880
	ds_read_u16 v1, v138 offset:2752
	s_waitcnt lgkmcnt(0)
; __device__ __forceinline__ int crow(int r, int hi) { return (r & 3) + 8 * (r >> 2) + 4 * hi; }
; __device__ __forceinline__ float bf2f(unsigned short v) { return __uint_as_float((unsigned)v << 16); }
; __device__ __forceinline__ unsigned f2bf(float f) { return pk2(f, 0.f) & 0xffffu; }
; __device__ __forceinline__ int crow(int r, int hi) { return (r & 3) + 8 * (r >> 2) + 4 * hi; }
; __device__ __forceinline__ float half_sum32(float v) {
; #pragma unroll
;     for (int o = 1; o < 32; o <<= 1) v += __shfl_xor(v, o);
;     return v;
; }
; __device__ __forceinline__ void gla_pass_c(LAS unsigned char* ldsl, const bf16_t* __restrict__ proj, const float* __restrict__ Btab, const float* __restrict__ Gst, const float* __restrict__ gout, bf16_t* __restrict__ mixed) {
;     ...
;         for (int i = 0; i < 16; ++i) { const int tr = crow(i, hh);
;             const float tot = half_sum32((o[0][i] * o[0][i] + o[1][i] * o[1][i]) + (o[2][i] * o[2][i] + o[3][i] * o[3][i]));
;             const float rr = __builtin_amdgcn_rsqf(tot * (1.0f / 128.0f) + EPS);
; #pragma unroll
;             for (int dvb = 0; dvb < 4; ++dvb) { const float g = bf2f(Lh[tr * 128 + 32 * dvb + r]);
;                 const float val = o[dvb][i] * rr * gn[dvb] * (g * __builtin_amdgcn_rcpf(1.0f + __expf(-g)));
;                 Lh[(32 + tr) * 128 + 32 * dvb + r] = (bf16_t)f2bf(val); } }
	v_lshlrev_b32_e32 v1, 16, v1
	v_mul_f32_e32 v2, 0xbfb8aa3b, v1
	v_exp_f32_e32 v2, v2
	s_nop 0
	v_add_f32_e32 v2, 1.0, v2
	v_rcp_f32_e32 v2, v2
	s_nop 0
	v_mul_f32_e32 v1, v2, v1
	v_mul_f32_e32 v0, v0, v1
	v_cvt_pk_bf16_f32 v0, v0, s0
	ds_write_b16 v138, v0 offset:10944
	v_mul_f32_e32 v0, v23, v23
	v_mul_f32_e32 v1, v39, v39
	v_fmac_f32_e32 v0, v7, v7
	v_fmac_f32_e32 v1, v55, v55
	v_add_f32_e32 v0, v0, v1
	s_nop 1
	v_add_f32_dpp v0, v0, v0 quad_perm:[1,0,3,2] row_mask:0xf bank_mask:0xf
	s_nop 1
	v_add_f32_dpp v0, v0, v0 quad_perm:[2,3,0,1] row_mask:0xf bank_mask:0xf
	s_nop 1
	v_add_f32_dpp v0, v0, v0 row_half_mirror row_mask:0xf bank_mask:0xf
	s_nop 1
	v_add_f32_dpp v0, v0, v0 row_mirror row_mask:0xf bank_mask:0xf
	s_waitcnt lgkmcnt(0)
	ds_bpermute_b32 v1, v137, v0
	s_waitcnt lgkmcnt(0)
	v_add_f32_e32 v0, v0, v1
	ds_read_u16 v1, v138 offset:2816
	v_fmamk_f32 v0, v0, 0x3c000000, v199
	v_rsq_f32_e32 v0, v0
	s_waitcnt lgkmcnt(0)
	v_lshlrev_b32_e32 v1, 16, v1
	v_mul_f32_e32 v3, 0xbfb8aa3b, v1
	v_exp_f32_e32 v3, v3
	v_mul_f32_e32 v2, v7, v0
	v_mul_f32_e32 v2, v113, v2
	v_add_f32_e32 v3, 1.0, v3
	v_rcp_f32_e32 v3, v3
	s_nop 0
	v_mul_f32_e32 v1, v3, v1
	v_mul_f32_e32 v1, v2, v1
	v_cvt_pk_bf16_f32 v1, v1, s0
	ds_write_b16 v138, v1 offset:11008
	ds_read_u16 v1, v138 offset:2880
	v_mul_f32_e32 v2, v23, v0
	v_mul_f32_e32 v2, v130, v2
	s_waitcnt lgkmcnt(0)
	v_lshlrev_b32_e32 v1, 16, v1
	v_mul_f32_e32 v3, 0xbfb8aa3b, v1
	v_exp_f32_e32 v3, v3
	s_nop 0
	v_add_f32_e32 v3, 1.0, v3
	v_rcp_f32_e32 v3, v3
	s_nop 0
	v_mul_f32_e32 v1, v3, v1
	v_mul_f32_e32 v1, v2, v1
	v_cvt_pk_bf16_f32 v1, v1, s0
	ds_write_b16 v138, v1 offset:11072
	ds_read_u16 v1, v138 offset:2944
	v_mul_f32_e32 v2, v55, v0
	v_mul_f32_e32 v2, v131, v2
	v_mul_f32_e32 v0, v39, v0
	v_mul_f32_e32 v0, v132, v0
	s_waitcnt lgkmcnt(0)
	v_lshlrev_b32_e32 v1, 16, v1
	v_mul_f32_e32 v3, 0xbfb8aa3b, v1
	v_exp_f32_e32 v3, v3
	s_nop 0
	v_add_f32_e32 v3, 1.0, v3
	v_rcp_f32_e32 v3, v3
	s_nop 0
	v_mul_f32_e32 v1, v3, v1
	v_mul_f32_e32 v1, v2, v1
	v_cvt_pk_bf16_f32 v1, v1, s0
	ds_write_b16 v138, v1 offset:11136
	ds_read_u16 v1, v138 offset:3008
	s_waitcnt lgkmcnt(0)
	v_lshlrev_b32_e32 v1, 16, v1
	v_mul_f32_e32 v2, 0xbfb8aa3b, v1
	v_exp_f32_e32 v2, v2
	s_nop 0
	v_add_f32_e32 v2, 1.0, v2
	v_rcp_f32_e32 v2, v2
	s_nop 0
	v_mul_f32_e32 v1, v2, v1
	v_mul_f32_e32 v0, v0, v1
	v_cvt_pk_bf16_f32 v0, v0, s0
	ds_write_b16 v138, v0 offset:11200
	v_mul_f32_e32 v0, v24, v24
	v_mul_f32_e32 v1, v40, v40
	v_fmac_f32_e32 v0, v8, v8
	v_fmac_f32_e32 v1, v56, v56
	v_add_f32_e32 v0, v0, v1
	s_nop 1
	v_add_f32_dpp v0, v0, v0 quad_perm:[1,0,3,2] row_mask:0xf bank_mask:0xf
	s_nop 1
	v_add_f32_dpp v0, v0, v0 quad_perm:[2,3,0,1] row_mask:0xf bank_mask:0xf
	s_nop 1
	v_add_f32_dpp v0, v0, v0 row_half_mirror row_mask:0xf bank_mask:0xf
	s_nop 1
	v_add_f32_dpp v0, v0, v0 row_mirror row_mask:0xf bank_mask:0xf
	s_waitcnt lgkmcnt(0)
	ds_bpermute_b32 v1, v137, v0
	s_waitcnt lgkmcnt(0)
	v_add_f32_e32 v0, v0, v1
	ds_read_u16 v1, v138 offset:4096
	v_fmamk_f32 v0, v0, 0x3c000000, v199
	v_rsq_f32_e32 v0, v0
	s_waitcnt lgkmcnt(0)
	v_lshlrev_b32_e32 v1, 16, v1
	v_mul_f32_e32 v3, 0xbfb8aa3b, v1
	v_exp_f32_e32 v3, v3
	v_mul_f32_e32 v2, v8, v0
	v_mul_f32_e32 v2, v113, v2
	v_add_f32_e32 v3, 1.0, v3
	v_rcp_f32_e32 v3, v3
	s_nop 0
	v_mul_f32_e32 v1, v3, v1
	v_mul_f32_e32 v1, v2, v1
	v_cvt_pk_bf16_f32 v1, v1, s0
	ds_write_b16 v138, v1 offset:12288
	ds_read_u16 v1, v138 offset:4160
	v_mul_f32_e32 v2, v24, v0
	v_mul_f32_e32 v2, v130, v2
	s_waitcnt lgkmcnt(0)
	v_lshlrev_b32_e32 v1, 16, v1
	v_mul_f32_e32 v3, 0xbfb8aa3b, v1
	v_exp_f32_e32 v3, v3
	s_nop 0
	v_add_f32_e32 v3, 1.0, v3
	v_rcp_f32_e32 v3, v3
	s_nop 0
	v_mul_f32_e32 v1, v3, v1
	v_mul_f32_e32 v1, v2, v1
	v_cvt_pk_bf16_f32 v1, v1, s0
	ds_write_b16 v138, v1 offset:12352
	ds_read_u16 v1, v138 offset:4224
	v_mul_f32_e32 v2, v56, v0
	v_mul_f32_e32 v2, v131, v2
	v_mul_f32_e32 v0, v40, v0
	v_mul_f32_e32 v0, v132, v0
	s_waitcnt lgkmcnt(0)
	v_lshlrev_b32_e32 v1, 16, v1
	v_mul_f32_e32 v3, 0xbfb8aa3b, v1
	v_exp_f32_e32 v3, v3
	s_nop 0
	v_add_f32_e32 v3, 1.0, v3
	v_rcp_f32_e32 v3, v3
	s_nop 0
	v_mul_f32_e32 v1, v3, v1
	v_mul_f32_e32 v1, v2, v1
	v_cvt_pk_bf16_f32 v1, v1, s0
	ds_write_b16 v138, v1 offset:12416
	ds_read_u16 v1, v138 offset:4288
	s_waitcnt lgkmcnt(0)
	v_lshlrev_b32_e32 v1, 16, v1
	v_mul_f32_e32 v2, 0xbfb8aa3b, v1
	v_exp_f32_e32 v2, v2
	s_nop 0
	v_add_f32_e32 v2, 1.0, v2
	v_rcp_f32_e32 v2, v2
	s_nop 0
	v_mul_f32_e32 v1, v2, v1
	v_mul_f32_e32 v0, v0, v1
	v_cvt_pk_bf16_f32 v0, v0, s0
	ds_write_b16 v138, v0 offset:12480
	v_mul_f32_e32 v0, v25, v25
	v_mul_f32_e32 v1, v41, v41
	v_fmac_f32_e32 v0, v9, v9
	v_fmac_f32_e32 v1, v57, v57
	v_add_f32_e32 v0, v0, v1
	s_nop 1
	v_add_f32_dpp v0, v0, v0 quad_perm:[1,0,3,2] row_mask:0xf bank_mask:0xf
	s_nop 1
	v_add_f32_dpp v0, v0, v0 quad_perm:[2,3,0,1] row_mask:0xf bank_mask:0xf
	s_nop 1
	v_add_f32_dpp v0, v0, v0 row_half_mirror row_mask:0xf bank_mask:0xf
	s_nop 1
	v_add_f32_dpp v0, v0, v0 row_mirror row_mask:0xf bank_mask:0xf
	s_waitcnt lgkmcnt(0)
	ds_bpermute_b32 v1, v137, v0
	s_waitcnt lgkmcnt(0)
	v_add_f32_e32 v0, v0, v1
	ds_read_u16 v1, v138 offset:4352
	v_fmamk_f32 v0, v0, 0x3c000000, v199
	v_rsq_f32_e32 v0, v0
	s_waitcnt lgkmcnt(0)
	v_lshlrev_b32_e32 v1, 16, v1
	v_mul_f32_e32 v3, 0xbfb8aa3b, v1
	v_exp_f32_e32 v3, v3
	v_mul_f32_e32 v2, v9, v0
	v_mul_f32_e32 v2, v113, v2
	v_add_f32_e32 v3, 1.0, v3
	v_rcp_f32_e32 v3, v3
	s_nop 0
	v_mul_f32_e32 v1, v3, v1
	v_mul_f32_e32 v1, v2, v1
	v_cvt_pk_bf16_f32 v1, v1, s0
	ds_write_b16 v138, v1 offset:12544
	ds_read_u16 v1, v138 offset:4416
	v_mul_f32_e32 v2, v25, v0
	v_mul_f32_e32 v2, v130, v2
	s_waitcnt lgkmcnt(0)
; __device__ __forceinline__ int crow(int r, int hi) { return (r & 3) + 8 * (r >> 2) + 4 * hi; }
; __device__ __forceinline__ float bf2f(unsigned short v) { return __uint_as_float((unsigned)v << 16); }
; __device__ __forceinline__ unsigned f2bf(float f) { return pk2(f, 0.f) & 0xffffu; }
; __device__ __forceinline__ int crow(int r, int hi) { return (r & 3) + 8 * (r >> 2) + 4 * hi; }
; __device__ __forceinline__ float half_sum32(float v) {
; #pragma unroll
;     for (int o = 1; o < 32; o <<= 1) v += __shfl_xor(v, o);
;     return v;
; }
; __device__ __forceinline__ void gla_pass_c(LAS unsigned char* ldsl, const bf16_t* __restrict__ proj, const float* __restrict__ Btab, const float* __restrict__ Gst, const float* __restrict__ gout, bf16_t* __restrict__ mixed) {
;     ...
;         for (int i = 0; i < 16; ++i) { const int tr = crow(i, hh);
;             const float tot = half_sum32((o[0][i] * o[0][i] + o[1][i] * o[1][i]) + (o[2][i] * o[2][i] + o[3][i] * o[3][i]));
;             const float rr = __builtin_amdgcn_rsqf(tot * (1.0f / 128.0f) + EPS);
; #pragma unroll
;             for (int dvb = 0; dvb < 4; ++dvb) { const float g = bf2f(Lh[tr * 128 + 32 * dvb + r]);
;                 const float val = o[dvb][i] * rr * gn[dvb] * (g * __builtin_amdgcn_rcpf(1.0f + __expf(-g)));
;                 Lh[(32 + tr) * 128 + 32 * dvb + r] = (bf16_t)f2bf(val); } }
	v_lshlrev_b32_e32 v1, 16, v1
	v_mul_f32_e32 v3, 0xbfb8aa3b, v1
	v_exp_f32_e32 v3, v3
	s_nop 0
	v_add_f32_e32 v3, 1.0, v3
	v_rcp_f32_e32 v3, v3
	s_nop 0
	v_mul_f32_e32 v1, v3, v1
	v_mul_f32_e32 v1, v2, v1
	v_cvt_pk_bf16_f32 v1, v1, s0
	ds_write_b16 v138, v1 offset:12608
	ds_read_u16 v1, v138 offset:4480
	v_mul_f32_e32 v2, v57, v0
	v_mul_f32_e32 v2, v131, v2
	v_mul_f32_e32 v0, v41, v0
	v_mul_f32_e32 v0, v132, v0
	s_waitcnt lgkmcnt(0)
	v_lshlrev_b32_e32 v1, 16, v1
	v_mul_f32_e32 v3, 0xbfb8aa3b, v1
	v_exp_f32_e32 v3, v3
	s_nop 0
	v_add_f32_e32 v3, 1.0, v3
	v_rcp_f32_e32 v3, v3
	s_nop 0
	v_mul_f32_e32 v1, v3, v1
	v_mul_f32_e32 v1, v2, v1
	v_cvt_pk_bf16_f32 v1, v1, s0
	ds_write_b16 v138, v1 offset:12672
	ds_read_u16 v1, v138 offset:4544
	s_waitcnt lgkmcnt(0)
	v_lshlrev_b32_e32 v1, 16, v1
	v_mul_f32_e32 v2, 0xbfb8aa3b, v1
	v_exp_f32_e32 v2, v2
	s_nop 0
	v_add_f32_e32 v2, 1.0, v2
	v_rcp_f32_e32 v2, v2
	s_nop 0
	v_mul_f32_e32 v1, v2, v1
	v_mul_f32_e32 v0, v0, v1
	v_cvt_pk_bf16_f32 v0, v0, s0
	ds_write_b16 v138, v0 offset:12736
	v_mul_f32_e32 v0, v26, v26
	v_mul_f32_e32 v1, v42, v42
	v_fmac_f32_e32 v0, v10, v10
	v_fmac_f32_e32 v1, v58, v58
	v_add_f32_e32 v0, v0, v1
	s_nop 1
	v_add_f32_dpp v0, v0, v0 quad_perm:[1,0,3,2] row_mask:0xf bank_mask:0xf
	s_nop 1
	v_add_f32_dpp v0, v0, v0 quad_perm:[2,3,0,1] row_mask:0xf bank_mask:0xf
	s_nop 1
	v_add_f32_dpp v0, v0, v0 row_half_mirror row_mask:0xf bank_mask:0xf
	s_nop 1
	v_add_f32_dpp v0, v0, v0 row_mirror row_mask:0xf bank_mask:0xf
	s_waitcnt lgkmcnt(0)
	ds_bpermute_b32 v1, v137, v0
	s_waitcnt lgkmcnt(0)
	v_add_f32_e32 v0, v0, v1
	ds_read_u16 v1, v138 offset:4608
	v_fmamk_f32 v0, v0, 0x3c000000, v199
	v_rsq_f32_e32 v0, v0
	s_waitcnt lgkmcnt(0)
	v_lshlrev_b32_e32 v1, 16, v1
	v_mul_f32_e32 v3, 0xbfb8aa3b, v1
	v_exp_f32_e32 v3, v3
	v_mul_f32_e32 v2, v10, v0
	v_mul_f32_e32 v2, v113, v2
	v_add_f32_e32 v3, 1.0, v3
	v_rcp_f32_e32 v3, v3
	s_nop 0
	v_mul_f32_e32 v1, v3, v1
	v_mul_f32_e32 v1, v2, v1
	v_cvt_pk_bf16_f32 v1, v1, s0
	ds_write_b16 v138, v1 offset:12800
	ds_read_u16 v1, v138 offset:4672
	v_mul_f32_e32 v2, v26, v0
	v_mul_f32_e32 v2, v130, v2
	s_waitcnt lgkmcnt(0)
	v_lshlrev_b32_e32 v1, 16, v1
	v_mul_f32_e32 v3, 0xbfb8aa3b, v1
	v_exp_f32_e32 v3, v3
	s_nop 0
	v_add_f32_e32 v3, 1.0, v3
	v_rcp_f32_e32 v3, v3
	s_nop 0
	v_mul_f32_e32 v1, v3, v1
	v_mul_f32_e32 v1, v2, v1
	v_cvt_pk_bf16_f32 v1, v1, s0
	ds_write_b16 v138, v1 offset:12864
	ds_read_u16 v1, v138 offset:4736
	v_mul_f32_e32 v2, v58, v0
	v_mul_f32_e32 v2, v131, v2
	v_mul_f32_e32 v0, v42, v0
	v_mul_f32_e32 v0, v132, v0
	s_waitcnt lgkmcnt(0)
	v_lshlrev_b32_e32 v1, 16, v1
	v_mul_f32_e32 v3, 0xbfb8aa3b, v1
	v_exp_f32_e32 v3, v3
	s_nop 0
	v_add_f32_e32 v3, 1.0, v3
	v_rcp_f32_e32 v3, v3
	s_nop 0
	v_mul_f32_e32 v1, v3, v1
	v_mul_f32_e32 v1, v2, v1
	v_cvt_pk_bf16_f32 v1, v1, s0
	ds_write_b16 v138, v1 offset:12928
	ds_read_u16 v1, v138 offset:4800
	s_waitcnt lgkmcnt(0)
	v_lshlrev_b32_e32 v1, 16, v1
	v_mul_f32_e32 v2, 0xbfb8aa3b, v1
	v_exp_f32_e32 v2, v2
	s_nop 0
	v_add_f32_e32 v2, 1.0, v2
	v_rcp_f32_e32 v2, v2
	s_nop 0
	v_mul_f32_e32 v1, v2, v1
	v_mul_f32_e32 v0, v0, v1
	v_cvt_pk_bf16_f32 v0, v0, s0
	ds_write_b16 v138, v0 offset:12992
	v_mul_f32_e32 v0, v27, v27
	v_mul_f32_e32 v1, v43, v43
	v_fmac_f32_e32 v0, v11, v11
	v_fmac_f32_e32 v1, v59, v59
	v_add_f32_e32 v0, v0, v1
	s_nop 1
	v_add_f32_dpp v0, v0, v0 quad_perm:[1,0,3,2] row_mask:0xf bank_mask:0xf
	s_nop 1
	v_add_f32_dpp v0, v0, v0 quad_perm:[2,3,0,1] row_mask:0xf bank_mask:0xf
	s_nop 1
	v_add_f32_dpp v0, v0, v0 row_half_mirror row_mask:0xf bank_mask:0xf
	s_nop 1
	v_add_f32_dpp v0, v0, v0 row_mirror row_mask:0xf bank_mask:0xf
	s_waitcnt lgkmcnt(0)
	ds_bpermute_b32 v1, v137, v0
	s_waitcnt lgkmcnt(0)
	v_add_f32_e32 v0, v0, v1
	ds_read_u16 v1, v138 offset:4864
	v_fmamk_f32 v0, v0, 0x3c000000, v199
	v_rsq_f32_e32 v0, v0
	s_waitcnt lgkmcnt(0)
	v_lshlrev_b32_e32 v1, 16, v1
	v_mul_f32_e32 v3, 0xbfb8aa3b, v1
	v_exp_f32_e32 v3, v3
	v_mul_f32_e32 v2, v11, v0
	v_mul_f32_e32 v2, v113, v2
	v_add_f32_e32 v3, 1.0, v3
	v_rcp_f32_e32 v3, v3
	s_nop 0
	v_mul_f32_e32 v1, v3, v1
	v_mul_f32_e32 v1, v2, v1
	v_cvt_pk_bf16_f32 v1, v1, s0
	ds_write_b16 v138, v1 offset:13056
	ds_read_u16 v1, v138 offset:4928
	v_mul_f32_e32 v2, v27, v0
	v_mul_f32_e32 v2, v130, v2
	s_waitcnt lgkmcnt(0)
	v_lshlrev_b32_e32 v1, 16, v1
	v_mul_f32_e32 v3, 0xbfb8aa3b, v1
	v_exp_f32_e32 v3, v3
	s_nop 0
	v_add_f32_e32 v3, 1.0, v3
	v_rcp_f32_e32 v3, v3
	s_nop 0
	v_mul_f32_e32 v1, v3, v1
	v_mul_f32_e32 v1, v2, v1
	v_cvt_pk_bf16_f32 v1, v1, s0
	ds_write_b16 v138, v1 offset:13120
	ds_read_u16 v1, v138 offset:4992
	v_mul_f32_e32 v2, v59, v0
	v_mul_f32_e32 v2, v131, v2
	v_mul_f32_e32 v0, v43, v0
	v_mul_f32_e32 v0, v132, v0
	s_waitcnt lgkmcnt(0)
	v_lshlrev_b32_e32 v1, 16, v1
	v_mul_f32_e32 v3, 0xbfb8aa3b, v1
	v_exp_f32_e32 v3, v3
	s_nop 0
	v_add_f32_e32 v3, 1.0, v3
	v_rcp_f32_e32 v3, v3
	s_nop 0
	v_mul_f32_e32 v1, v3, v1
	v_mul_f32_e32 v1, v2, v1
	v_cvt_pk_bf16_f32 v1, v1, s0
	ds_write_b16 v138, v1 offset:13184
	ds_read_u16 v1, v138 offset:5056
	s_waitcnt lgkmcnt(0)
	v_lshlrev_b32_e32 v1, 16, v1
	v_mul_f32_e32 v2, 0xbfb8aa3b, v1
	v_exp_f32_e32 v2, v2
	s_nop 0
	v_add_f32_e32 v2, 1.0, v2
	v_rcp_f32_e32 v2, v2
	s_nop 0
	v_mul_f32_e32 v1, v2, v1
	v_mul_f32_e32 v0, v0, v1
	v_cvt_pk_bf16_f32 v0, v0, s0
	ds_write_b16 v138, v0 offset:13248
	v_mul_f32_e32 v0, v28, v28
	v_mul_f32_e32 v1, v44, v44
	v_fmac_f32_e32 v0, v12, v12
	v_fmac_f32_e32 v1, v60, v60
	v_add_f32_e32 v0, v0, v1
	s_nop 1
	v_add_f32_dpp v0, v0, v0 quad_perm:[1,0,3,2] row_mask:0xf bank_mask:0xf
	s_nop 1
	v_add_f32_dpp v0, v0, v0 quad_perm:[2,3,0,1] row_mask:0xf bank_mask:0xf
	s_nop 1
	v_add_f32_dpp v0, v0, v0 row_half_mirror row_mask:0xf bank_mask:0xf
	s_nop 1
	v_add_f32_dpp v0, v0, v0 row_mirror row_mask:0xf bank_mask:0xf
	s_waitcnt lgkmcnt(0)
; __device__ __forceinline__ int crow(int r, int hi) { return (r & 3) + 8 * (r >> 2) + 4 * hi; }
; __device__ __forceinline__ float bf2f(unsigned short v) { return __uint_as_float((unsigned)v << 16); }
; __device__ __forceinline__ unsigned f2bf(float f) { return pk2(f, 0.f) & 0xffffu; }
; __device__ __forceinline__ int crow(int r, int hi) { return (r & 3) + 8 * (r >> 2) + 4 * hi; }
; __device__ __forceinline__ float half_sum32(float v) {
; #pragma unroll
;     for (int o = 1; o < 32; o <<= 1) v += __shfl_xor(v, o);
;     return v;
; }
; __device__ __forceinline__ void gla_pass_c(LAS unsigned char* ldsl, const bf16_t* __restrict__ proj, const float* __restrict__ Btab, const float* __restrict__ Gst, const float* __restrict__ gout, bf16_t* __restrict__ mixed) {
;     ...
;         for (int i = 0; i < 16; ++i) { const int tr = crow(i, hh);
;             const float tot = half_sum32((o[0][i] * o[0][i] + o[1][i] * o[1][i]) + (o[2][i] * o[2][i] + o[3][i] * o[3][i]));
;             const float rr = __builtin_amdgcn_rsqf(tot * (1.0f / 128.0f) + EPS);
; #pragma unroll
;             for (int dvb = 0; dvb < 4; ++dvb) { const float g = bf2f(Lh[tr * 128 + 32 * dvb + r]);
;                 const float val = o[dvb][i] * rr * gn[dvb] * (g * __builtin_amdgcn_rcpf(1.0f + __expf(-g)));
;                 Lh[(32 + tr) * 128 + 32 * dvb + r] = (bf16_t)f2bf(val); } }
	ds_bpermute_b32 v1, v137, v0
	s_waitcnt lgkmcnt(0)
	v_add_f32_e32 v0, v0, v1
	ds_read_u16 v1, v138 offset:6144
	v_fmamk_f32 v0, v0, 0x3c000000, v199
	v_rsq_f32_e32 v0, v0
	s_waitcnt lgkmcnt(0)
	v_lshlrev_b32_e32 v1, 16, v1
	v_mul_f32_e32 v3, 0xbfb8aa3b, v1
	v_exp_f32_e32 v3, v3
	v_mul_f32_e32 v2, v12, v0
	v_mul_f32_e32 v2, v113, v2
	v_add_f32_e32 v3, 1.0, v3
	v_rcp_f32_e32 v3, v3
	s_nop 0
	v_mul_f32_e32 v1, v3, v1
	v_mul_f32_e32 v1, v2, v1
	v_cvt_pk_bf16_f32 v1, v1, s0
	ds_write_b16 v138, v1 offset:14336
	ds_read_u16 v1, v138 offset:6208
	v_mul_f32_e32 v2, v28, v0
	v_mul_f32_e32 v2, v130, v2
	s_waitcnt lgkmcnt(0)
	v_lshlrev_b32_e32 v1, 16, v1
	v_mul_f32_e32 v3, 0xbfb8aa3b, v1
	v_exp_f32_e32 v3, v3
	s_nop 0
	v_add_f32_e32 v3, 1.0, v3
	v_rcp_f32_e32 v3, v3
	s_nop 0
	v_mul_f32_e32 v1, v3, v1
	v_mul_f32_e32 v1, v2, v1
	v_cvt_pk_bf16_f32 v1, v1, s0
	ds_write_b16 v138, v1 offset:14400
	ds_read_u16 v1, v138 offset:6272
	v_mul_f32_e32 v2, v60, v0
	v_mul_f32_e32 v2, v131, v2
	v_mul_f32_e32 v0, v44, v0
	v_mul_f32_e32 v0, v132, v0
	s_waitcnt lgkmcnt(0)
	v_lshlrev_b32_e32 v1, 16, v1
	v_mul_f32_e32 v3, 0xbfb8aa3b, v1
	v_exp_f32_e32 v3, v3
	s_nop 0
	v_add_f32_e32 v3, 1.0, v3
	v_rcp_f32_e32 v3, v3
	s_nop 0
	v_mul_f32_e32 v1, v3, v1
	v_mul_f32_e32 v1, v2, v1
	v_cvt_pk_bf16_f32 v1, v1, s0
	ds_write_b16 v138, v1 offset:14464
	ds_read_u16 v1, v138 offset:6336
	s_waitcnt lgkmcnt(0)
	v_lshlrev_b32_e32 v1, 16, v1
	v_mul_f32_e32 v2, 0xbfb8aa3b, v1
	v_exp_f32_e32 v2, v2
	s_nop 0
	v_add_f32_e32 v2, 1.0, v2
	v_rcp_f32_e32 v2, v2
	s_nop 0
	v_mul_f32_e32 v1, v2, v1
	v_mul_f32_e32 v0, v0, v1
	v_cvt_pk_bf16_f32 v0, v0, s0
	ds_write_b16 v138, v0 offset:14528
	v_mul_f32_e32 v0, v29, v29
	v_mul_f32_e32 v1, v45, v45
	v_fmac_f32_e32 v0, v13, v13
	v_fmac_f32_e32 v1, v61, v61
	v_add_f32_e32 v0, v0, v1
	s_nop 1
	v_add_f32_dpp v0, v0, v0 quad_perm:[1,0,3,2] row_mask:0xf bank_mask:0xf
	s_nop 1
	v_add_f32_dpp v0, v0, v0 quad_perm:[2,3,0,1] row_mask:0xf bank_mask:0xf
	s_nop 1
	v_add_f32_dpp v0, v0, v0 row_half_mirror row_mask:0xf bank_mask:0xf
	s_nop 1
	v_add_f32_dpp v0, v0, v0 row_mirror row_mask:0xf bank_mask:0xf
	s_waitcnt lgkmcnt(0)
	ds_bpermute_b32 v1, v137, v0
	s_waitcnt lgkmcnt(0)
	v_add_f32_e32 v0, v0, v1
	ds_read_u16 v1, v138 offset:6400
	v_fmamk_f32 v0, v0, 0x3c000000, v199
	v_rsq_f32_e32 v0, v0
	s_waitcnt lgkmcnt(0)
	v_lshlrev_b32_e32 v1, 16, v1
	v_mul_f32_e32 v3, 0xbfb8aa3b, v1
	v_exp_f32_e32 v3, v3
	v_mul_f32_e32 v2, v13, v0
	v_mul_f32_e32 v2, v113, v2
	v_add_f32_e32 v3, 1.0, v3
	v_rcp_f32_e32 v3, v3
	s_nop 0
	v_mul_f32_e32 v1, v3, v1
	v_mul_f32_e32 v1, v2, v1
	v_cvt_pk_bf16_f32 v1, v1, s0
	ds_write_b16 v138, v1 offset:14592
	ds_read_u16 v1, v138 offset:6464
	v_mul_f32_e32 v2, v29, v0
	v_mul_f32_e32 v2, v130, v2
	s_waitcnt lgkmcnt(0)
	v_lshlrev_b32_e32 v1, 16, v1
	v_mul_f32_e32 v3, 0xbfb8aa3b, v1
	v_exp_f32_e32 v3, v3
	s_nop 0
	v_add_f32_e32 v3, 1.0, v3
	v_rcp_f32_e32 v3, v3
	s_nop 0
	v_mul_f32_e32 v1, v3, v1
	v_mul_f32_e32 v1, v2, v1
	v_cvt_pk_bf16_f32 v1, v1, s0
	ds_write_b16 v138, v1 offset:14656
	ds_read_u16 v1, v138 offset:6528
	v_mul_f32_e32 v2, v61, v0
	v_mul_f32_e32 v2, v131, v2
	v_mul_f32_e32 v0, v45, v0
	v_mul_f32_e32 v0, v132, v0
	s_waitcnt lgkmcnt(0)
	v_lshlrev_b32_e32 v1, 16, v1
	v_mul_f32_e32 v3, 0xbfb8aa3b, v1
	v_exp_f32_e32 v3, v3
	s_nop 0
	v_add_f32_e32 v3, 1.0, v3
	v_rcp_f32_e32 v3, v3
	s_nop 0
	v_mul_f32_e32 v1, v3, v1
	v_mul_f32_e32 v1, v2, v1
	v_cvt_pk_bf16_f32 v1, v1, s0
	ds_write_b16 v138, v1 offset:14720
	ds_read_u16 v1, v138 offset:6592
	s_waitcnt lgkmcnt(0)
	v_lshlrev_b32_e32 v1, 16, v1
	v_mul_f32_e32 v2, 0xbfb8aa3b, v1
	v_exp_f32_e32 v2, v2
	s_nop 0
	v_add_f32_e32 v2, 1.0, v2
	v_rcp_f32_e32 v2, v2
	s_nop 0
	v_mul_f32_e32 v1, v2, v1
	v_mul_f32_e32 v0, v0, v1
	v_cvt_pk_bf16_f32 v0, v0, s0
	ds_write_b16 v138, v0 offset:14784
	v_mul_f32_e32 v0, v30, v30
	v_mul_f32_e32 v1, v46, v46
	v_fmac_f32_e32 v0, v14, v14
	v_fmac_f32_e32 v1, v62, v62
	v_add_f32_e32 v0, v0, v1
	s_nop 1
	v_add_f32_dpp v0, v0, v0 quad_perm:[1,0,3,2] row_mask:0xf bank_mask:0xf
	s_nop 1
	v_add_f32_dpp v0, v0, v0 quad_perm:[2,3,0,1] row_mask:0xf bank_mask:0xf
	s_nop 1
	v_add_f32_dpp v0, v0, v0 row_half_mirror row_mask:0xf bank_mask:0xf
	s_nop 1
	v_add_f32_dpp v0, v0, v0 row_mirror row_mask:0xf bank_mask:0xf
	s_waitcnt lgkmcnt(0)
	ds_bpermute_b32 v1, v137, v0
	s_waitcnt lgkmcnt(0)
	v_add_f32_e32 v0, v0, v1
	ds_read_u16 v1, v138 offset:6656
	v_fmamk_f32 v0, v0, 0x3c000000, v199
	v_rsq_f32_e32 v0, v0
	s_waitcnt lgkmcnt(0)
	v_lshlrev_b32_e32 v1, 16, v1
	v_mul_f32_e32 v3, 0xbfb8aa3b, v1
	v_exp_f32_e32 v3, v3
	v_mul_f32_e32 v2, v14, v0
	v_mul_f32_e32 v2, v113, v2
	v_add_f32_e32 v3, 1.0, v3
	v_rcp_f32_e32 v3, v3
	s_nop 0
	v_mul_f32_e32 v1, v3, v1
	v_mul_f32_e32 v1, v2, v1
	v_cvt_pk_bf16_f32 v1, v1, s0
	ds_write_b16 v138, v1 offset:14848
	ds_read_u16 v1, v138 offset:6720
	v_mul_f32_e32 v2, v30, v0
	v_mul_f32_e32 v2, v130, v2
	s_waitcnt lgkmcnt(0)
; #define LAS __attribute__((address_space(3)))
; __device__ __forceinline__ int crow(int r, int hi) { return (r & 3) + 8 * (r >> 2) + 4 * hi; }
; __device__ __forceinline__ float bf2f(unsigned short v) { return __uint_as_float((unsigned)v << 16); }
; __device__ __forceinline__ unsigned f2bf(float f) { return pk2(f, 0.f) & 0xffffu; }
; __device__ __forceinline__ int crow(int r, int hi) { return (r & 3) + 8 * (r >> 2) + 4 * hi; }
; __device__ __forceinline__ float half_sum32(float v) {
; #pragma unroll
;     for (int o = 1; o < 32; o <<= 1) v += __shfl_xor(v, o);
;     return v;
; }
; __device__ __forceinline__ void gla_pass_c(LAS unsigned char* ldsl, const bf16_t* __restrict__ proj, const float* __restrict__ Btab, const float* __restrict__ Gst, const float* __restrict__ gout, bf16_t* __restrict__ mixed) {
;     ...
;         for (int i = 0; i < 16; ++i) { const int tr = crow(i, hh);
;             const float tot = half_sum32((o[0][i] * o[0][i] + o[1][i] * o[1][i]) + (o[2][i] * o[2][i] + o[3][i] * o[3][i]));
;             const float rr = __builtin_amdgcn_rsqf(tot * (1.0f / 128.0f) + EPS);
; #pragma unroll
;             for (int dvb = 0; dvb < 4; ++dvb) { const float g = bf2f(Lh[tr * 128 + 32 * dvb + r]);
;                 const float val = o[dvb][i] * rr * gn[dvb] * (g * __builtin_amdgcn_rcpf(1.0f + __expf(-g)));
;                 Lh[(32 + tr) * 128 + 32 * dvb + r] = (bf16_t)f2bf(val); } }
;         { bf16_t* mp = mixed + (row0 + 32 * tb + crw) * DM + h * 128 + ccl * 8;
; #pragma unroll
;           for (int i = 0; i < 8; ++i) *(u32x4*)(mp + (size_t)(4 * i) * DM) = *(const LAS u32x4*)(Lw + (32 + 4 * i + crw) * 256 + ccl * 16); }
	v_lshlrev_b32_e32 v1, 16, v1
	v_mul_f32_e32 v3, 0xbfb8aa3b, v1
	v_exp_f32_e32 v3, v3
	s_nop 0
	v_add_f32_e32 v3, 1.0, v3
	v_rcp_f32_e32 v3, v3
	s_nop 0
	v_mul_f32_e32 v1, v3, v1
	v_mul_f32_e32 v1, v2, v1
	v_cvt_pk_bf16_f32 v1, v1, s0
	ds_write_b16 v138, v1 offset:14912
	ds_read_u16 v1, v138 offset:6784
	v_mul_f32_e32 v2, v62, v0
	v_mul_f32_e32 v2, v131, v2
	v_mul_f32_e32 v0, v46, v0
	v_mul_f32_e32 v0, v132, v0
	s_waitcnt lgkmcnt(0)
	v_lshlrev_b32_e32 v1, 16, v1
	v_mul_f32_e32 v3, 0xbfb8aa3b, v1
	v_exp_f32_e32 v3, v3
	s_nop 0
	v_add_f32_e32 v3, 1.0, v3
	v_rcp_f32_e32 v3, v3
	s_nop 0
	v_mul_f32_e32 v1, v3, v1
	v_mul_f32_e32 v1, v2, v1
	v_cvt_pk_bf16_f32 v1, v1, s0
	ds_write_b16 v138, v1 offset:14976
	ds_read_u16 v1, v138 offset:6848
	s_waitcnt lgkmcnt(0)
	v_lshlrev_b32_e32 v1, 16, v1
	v_mul_f32_e32 v2, 0xbfb8aa3b, v1
	v_exp_f32_e32 v2, v2
	s_nop 0
	v_add_f32_e32 v2, 1.0, v2
	v_rcp_f32_e32 v2, v2
	s_nop 0
	v_mul_f32_e32 v1, v2, v1
	v_mul_f32_e32 v0, v0, v1
	v_cvt_pk_bf16_f32 v0, v0, s0
	ds_write_b16 v138, v0 offset:15040
	v_mul_f32_e32 v0, v31, v31
	v_mul_f32_e32 v1, v47, v47
	v_fmac_f32_e32 v0, v15, v15
	v_fmac_f32_e32 v1, v63, v63
	v_add_f32_e32 v0, v0, v1
	s_nop 1
	v_add_f32_dpp v0, v0, v0 quad_perm:[1,0,3,2] row_mask:0xf bank_mask:0xf
	s_nop 1
	v_add_f32_dpp v0, v0, v0 quad_perm:[2,3,0,1] row_mask:0xf bank_mask:0xf
	s_nop 1
	v_add_f32_dpp v0, v0, v0 row_half_mirror row_mask:0xf bank_mask:0xf
	s_nop 1
	v_add_f32_dpp v0, v0, v0 row_mirror row_mask:0xf bank_mask:0xf
	s_waitcnt lgkmcnt(0)
	ds_bpermute_b32 v1, v137, v0
	s_waitcnt lgkmcnt(0)
	v_add_f32_e32 v0, v0, v1
	ds_read_u16 v1, v138 offset:6912
	v_fmamk_f32 v0, v0, 0x3c000000, v199
	v_rsq_f32_e32 v0, v0
	s_waitcnt lgkmcnt(0)
	v_lshlrev_b32_e32 v1, 16, v1
	v_mul_f32_e32 v3, 0xbfb8aa3b, v1
	v_exp_f32_e32 v3, v3
	v_mul_f32_e32 v2, v15, v0
	v_mul_f32_e32 v2, v113, v2
	v_add_f32_e32 v3, 1.0, v3
	v_rcp_f32_e32 v3, v3
	s_nop 0
	v_mul_f32_e32 v1, v3, v1
	v_mul_f32_e32 v1, v2, v1
	v_cvt_pk_bf16_f32 v1, v1, s0
	ds_write_b16 v138, v1 offset:15104
	ds_read_u16 v1, v138 offset:6976
	v_mul_f32_e32 v2, v31, v0
	v_mul_f32_e32 v2, v130, v2
	s_waitcnt lgkmcnt(0)
	v_lshlrev_b32_e32 v1, 16, v1
	v_mul_f32_e32 v3, 0xbfb8aa3b, v1
	v_exp_f32_e32 v3, v3
	s_nop 0
	v_add_f32_e32 v3, 1.0, v3
	v_rcp_f32_e32 v3, v3
	s_nop 0
	v_mul_f32_e32 v1, v3, v1
	v_mul_f32_e32 v1, v2, v1
	v_cvt_pk_bf16_f32 v1, v1, s0
	ds_write_b16 v138, v1 offset:15168
	ds_read_u16 v1, v138 offset:7040
	v_mul_f32_e32 v2, v63, v0
	v_mul_f32_e32 v2, v131, v2
	v_mul_f32_e32 v0, v47, v0
	v_mul_f32_e32 v0, v132, v0
	s_waitcnt lgkmcnt(0)
	v_lshlrev_b32_e32 v1, 16, v1
	v_mul_f32_e32 v3, 0xbfb8aa3b, v1
	v_exp_f32_e32 v3, v3
	s_nop 0
	v_add_f32_e32 v3, 1.0, v3
	v_rcp_f32_e32 v3, v3
	s_nop 0
	v_mul_f32_e32 v1, v3, v1
	v_mul_f32_e32 v1, v2, v1
	v_cvt_pk_bf16_f32 v1, v1, s0
	ds_write_b16 v138, v1 offset:15232
	ds_read_u16 v1, v138 offset:7104
	s_waitcnt lgkmcnt(0)
	v_lshlrev_b32_e32 v1, 16, v1
	v_mul_f32_e32 v2, 0xbfb8aa3b, v1
	v_exp_f32_e32 v2, v2
	s_nop 0
	v_add_f32_e32 v2, 1.0, v2
	v_rcp_f32_e32 v2, v2
	s_nop 0
	v_mul_f32_e32 v1, v2, v1
	v_mul_f32_e32 v0, v0, v1
	v_cvt_pk_bf16_f32 v0, v0, s0
	ds_write_b16 v138, v0 offset:15296
	v_lshlrev_b64 v[0:1], 11, v[122:123]
	v_lshl_add_u64 v[0:1], s[54:55], 0, v[0:1]
	v_lshl_add_u64 v[0:1], v[0:1], 0, v[160:161]
	v_lshl_add_u64 v[4:5], v[0:1], 0, v[120:121]
	ds_read_b128 v[0:3], v140 offset:8192
	v_add_co_u32_e32 v6, vcc, s2, v4
	s_movk_i32 s2, 0x6000
	s_nop 0
	v_addc_co_u32_e32 v7, vcc, 0, v5, vcc
	s_waitcnt lgkmcnt(0)
	global_store_dwordx4 v[4:5], v[0:3], off
	ds_read_b128 v[0:3], v140 offset:9216
	s_waitcnt lgkmcnt(0)
	global_store_dwordx4 v[6:7], v[0:3], off
	ds_read_b128 v[0:3], v140 offset:10240
	v_add_co_u32_e32 v6, vcc, s49, v4
	s_nop 1
	v_addc_co_u32_e32 v7, vcc, 0, v5, vcc
	s_waitcnt lgkmcnt(0)
	global_store_dwordx4 v[6:7], v[0:3], off
	ds_read_b128 v[0:3], v140 offset:11264
	v_add_co_u32_e32 v6, vcc, s2, v4
	s_mov_b32 s2, 0xa000
	s_nop 0
	v_addc_co_u32_e32 v7, vcc, 0, v5, vcc
	s_waitcnt lgkmcnt(0)
	global_store_dwordx4 v[6:7], v[0:3], off
	ds_read_b128 v[0:3], v140 offset:12288
	v_add_co_u32_e32 v6, vcc, s42, v4
	s_nop 1
	v_addc_co_u32_e32 v7, vcc, 0, v5, vcc
	s_waitcnt lgkmcnt(0)
	global_store_dwordx4 v[6:7], v[0:3], off
	ds_read_b128 v[0:3], v140 offset:13312
	v_add_co_u32_e32 v6, vcc, s2, v4
	s_movk_i32 s2, 0x7ff
	s_nop 0
	v_addc_co_u32_e32 v7, vcc, 0, v5, vcc
	s_waitcnt lgkmcnt(0)
	global_store_dwordx4 v[6:7], v[0:3], off
	ds_read_b128 v[0:3], v140 offset:14336
	v_add_co_u32_e32 v6, vcc, 0xc000, v4
	s_nop 1
	v_addc_co_u32_e32 v7, vcc, 0, v5, vcc
	s_waitcnt lgkmcnt(0)
	global_store_dwordx4 v[6:7], v[0:3], off
	ds_read_b128 v[0:3], v140 offset:15360
	v_add_co_u32_e32 v4, vcc, 0xe000, v4
	s_nop 1
	v_addc_co_u32_e32 v5, vcc, 0, v5, vcc
	s_waitcnt lgkmcnt(0)
	global_store_dwordx4 v[4:5], v[0:3], off
	v_cmp_lt_i32_e32 vcc, s2, v111
	s_or_b64 s[40:41], vcc, s[40:41]
	v_add_u32_e32 v0, 0x800, v111
	v_mov_b32_e32 v111, v0
	s_andn2_b64 exec, exec, s[40:41]
	s_cbranch_execz .LBB0_880
